# write-through (sc1) stores also in the norm phases (bf16 h rows) and the final norm output; on top of v71
# baseline (speedup 1.0000x reference)
.LBB0_79:
	global_load_dwordx4 v[2:5], v[114:115], off offset:-4096
	global_load_dwordx4 v[6:9], v[114:115], off offset:-3072
	global_load_dwordx4 v[10:13], v[114:115], off offset:-2048
	global_load_dwordx4 v[14:17], v[114:115], off offset:1024
	global_load_dwordx4 v[18:21], v[114:115], off
	global_load_dwordx4 v[22:25], v[114:115], off offset:-1024
	global_load_dwordx4 v[26:29], v[114:115], off offset:2048
	global_load_dwordx4 v[30:33], v[114:115], off offset:3072
	s_ashr_i32 s23, s22, 31
	s_lshl_b64 s[4:5], s[22:23], 13
	v_lshl_add_u64 v[66:67], v[100:101], 0, s[4:5]
	global_load_dwordx4 v[38:41], v[104:105], off
	global_load_dwordx4 v[34:37], v[104:105], off offset:1024
	global_load_dwordx4 v[46:49], v[104:105], off offset:2048
	global_load_dwordx4 v[42:45], v[104:105], off offset:3072
	global_load_dwordx4 v[54:57], v[106:107], off
	global_load_dwordx4 v[50:53], v[108:109], off
	global_load_dwordx4 v[62:65], v[110:111], off
	global_load_dwordx4 v[58:61], v[112:113], off
	global_load_dwordx4 v[70:73], v[66:67], off offset:2048
	global_load_dwordx4 v[94:97], v[66:67], off
	global_load_dwordx4 v[90:93], v[66:67], off offset:1024
	global_load_dwordx4 v[82:85], v[66:67], off offset:3072
	v_add_co_u32_e32 v66, vcc, s19, v66
	s_lshl_b64 s[6:7], s[22:23], 12
	s_nop 0
	v_addc_co_u32_e32 v67, vcc, 0, v67, vcc
	global_load_dwordx4 v[74:77], v[66:67], off offset:1024
	global_load_dwordx4 v[86:89], v[66:67], off
	global_load_dwordx4 v[78:81], v[66:67], off offset:2048
	s_nop 0
	global_load_dwordx4 v[66:69], v[66:67], off offset:3072
	v_lshl_add_u64 v[118:119], v[102:103], 0, s[6:7]
	s_add_i32 s27, s27, s18
	s_add_i32 s26, s26, s18
	s_add_i32 s22, s27, s86
	s_add_i32 s23, s3, s26
	v_lshl_add_u64 v[114:115], v[114:115], 0, s[0:1]
	s_cmpk_lt_i32 s23, 0x4000
	s_waitcnt vmcnt(23)
	v_mov_b32_e32 v132, v3
	s_waitcnt vmcnt(22)
	v_mov_b32_e32 v133, v7
	v_mov_b32_e32 v136, v5
	v_mov_b32_e32 v137, v9
	v_mov_b32_e32 v130, v2
	v_mov_b32_e32 v131, v6
	v_mov_b32_e32 v134, v4
	v_mov_b32_e32 v135, v8
	s_waitcnt vmcnt(21)
	v_pk_mul_f32 v[138:139], v[12:13], v[12:13]
	v_pk_mul_f32 v[140:141], v[10:11], v[10:11]
	s_waitcnt vmcnt(20)
	v_pk_mul_f32 v[142:143], v[16:17], v[16:17]
	v_pk_mul_f32 v[144:145], v[14:15], v[14:15]
	s_waitcnt vmcnt(19)
	v_mul_f32_e32 v153, v21, v21
	s_waitcnt vmcnt(18)
	v_mul_f32_e32 v146, v23, v23
	v_mul_f32_e32 v148, v25, v25
	s_waitcnt vmcnt(17)
	v_mul_f32_e32 v150, v27, v27
	v_mul_f32_e32 v152, v29, v29
	v_pk_mul_f32 v[132:133], v[132:133], v[132:133]
	v_pk_mul_f32 v[136:137], v[136:137], v[136:137]
	v_mul_f32_e32 v129, v20, v20
	s_waitcnt vmcnt(16)
	v_mul_f32_e32 v156, v32, v32
	v_mul_f32_e32 v157, v33, v33
	v_pk_mov_b32 v[154:155], v[140:141], v[138:139] op_sel:[1,0]
	v_mov_b32_e32 v141, v139
	v_pk_mov_b32 v[138:139], v[144:145], v[142:143] op_sel:[1,0]
	v_mov_b32_e32 v145, v143
	v_pk_fma_f32 v[142:143], v[22:23], v[22:23], v[146:147] op_sel_hi:[1,1,0]
	v_pk_fma_f32 v[146:147], v[24:25], v[24:25], v[148:149] op_sel_hi:[1,1,0]
	v_pk_fma_f32 v[148:149], v[26:27], v[26:27], v[150:151] op_sel_hi:[1,1,0]
	v_pk_fma_f32 v[150:151], v[28:29], v[28:29], v[152:153] op_sel_hi:[1,1,0]
	v_pk_fma_f32 v[130:131], v[130:131], v[130:131], v[132:133]
	v_pk_fma_f32 v[132:133], v[134:135], v[134:135], v[136:137]
	v_pk_add_f32 v[134:135], v[154:155], v[140:141]
	v_mov_b32_e32 v143, v129
	v_mov_b32_e32 v147, v153
	v_mov_b32_e32 v149, v156
	v_mov_b32_e32 v151, v157
	v_pk_add_f32 v[130:131], v[130:131], v[132:133]
	v_mul_f32_e32 v158, v19, v19
	v_mul_f32_e32 v161, v18, v18
	v_pk_add_f32 v[136:137], v[138:139], v[144:145]
	v_pk_add_f32 v[132:133], v[142:143], v[146:147]
	v_pk_add_f32 v[138:139], v[148:149], v[150:151]
	v_pk_add_f32 v[134:135], v[134:135], v[134:135] op_sel:[0,1] op_sel_hi:[1,0]
	s_waitcnt vmcnt(7)
	v_pk_mul_f32 v[140:141], v[72:73], v[72:73]
	v_pk_mul_f32 v[142:143], v[70:71], v[70:71]
	s_waitcnt vmcnt(6)
	v_mov_b32_e32 v146, v95
	s_waitcnt vmcnt(5)
	v_mov_b32_e32 v147, v91
	v_mov_b32_e32 v150, v97
	v_mov_b32_e32 v151, v93
	v_pk_add_f32 v[130:131], v[130:131], v[130:131] op_sel:[0,1] op_sel_hi:[1,0]
	v_mov_b32_e32 v144, v94
	v_mov_b32_e32 v145, v90
	v_mov_b32_e32 v148, v96
	v_mov_b32_e32 v149, v92
	v_mov_b32_e32 v135, v158
	v_pk_mov_b32 v[156:157], v[142:143], v[140:141] op_sel:[1,0]
	v_mov_b32_e32 v143, v141
	v_pk_mul_f32 v[140:141], v[146:147], v[146:147]
	v_pk_mul_f32 v[146:147], v[150:151], v[150:151]
	v_mov_b32_e32 v131, v161
	v_pk_fma_f32 v[140:141], v[144:145], v[144:145], v[140:141]
	v_pk_fma_f32 v[144:145], v[148:149], v[148:149], v[146:147]
	v_pk_add_f32 v[130:131], v[130:131], v[134:135]
	s_waitcnt vmcnt(4)
	v_mul_f32_e32 v152, v83, v83
	v_mul_f32_e32 v154, v85, v85
	v_pk_add_f32 v[142:143], v[156:157], v[142:143]
	v_pk_add_f32 v[134:135], v[140:141], v[144:145]
	v_pk_add_f32 v[130:131], v[130:131], v[132:133]
	v_mul_f32_e32 v163, v30, v30
	v_mul_f32_e32 v159, v31, v31
	v_pk_add_f32 v[136:137], v[136:137], v[136:137] op_sel:[0,1] op_sel_hi:[1,0]
	v_pk_fma_f32 v[152:153], v[82:83], v[82:83], v[152:153] op_sel_hi:[1,1,0]
	v_pk_fma_f32 v[154:155], v[84:85], v[84:85], v[154:155] op_sel_hi:[1,1,0]
	s_waitcnt vmcnt(2)
	v_mul_f32_e32 v166, v87, v87
	v_mul_f32_e32 v167, v86, v86
	v_pk_add_f32 v[142:143], v[142:143], v[142:143] op_sel:[0,1] op_sel_hi:[1,0]
	v_pk_add_f32 v[134:135], v[134:135], v[134:135] op_sel:[0,1] op_sel_hi:[1,0]
	v_pk_add_f32 v[130:131], v[130:131], v[130:131] op_sel:[0,1] op_sel_hi:[1,0]
	v_mov_b32_e32 v137, v159
	v_pk_mul_f32 v[150:151], v[76:77], v[76:77]
	v_pk_mul_f32 v[158:159], v[74:75], v[74:75]
	v_mul_f32_e32 v153, v88, v88
	v_mul_f32_e32 v155, v89, v89
	v_mov_b32_e32 v143, v166
	v_mov_b32_e32 v135, v167
	v_mov_b32_e32 v131, v163
	v_pk_mov_b32 v[146:147], v[158:159], v[150:151] op_sel:[1,0]
	v_mov_b32_e32 v159, v151
	v_pk_add_f32 v[140:141], v[152:153], v[154:155]
	v_pk_add_f32 v[134:135], v[134:135], v[142:143]
	v_pk_add_f32 v[130:131], v[130:131], v[136:137]
	s_waitcnt vmcnt(1)
	v_mul_f32_e32 v160, v79, v79
	v_mul_f32_e32 v162, v81, v81
	v_pk_add_f32 v[144:145], v[146:147], v[158:159]
	v_pk_add_f32 v[134:135], v[134:135], v[140:141]
	v_pk_add_f32 v[130:131], v[130:131], v[138:139]
	s_waitcnt vmcnt(0)
	v_mul_f32_e32 v164, v68, v68
	v_mul_f32_e32 v165, v69, v69
	v_mul_f32_e32 v168, v67, v67
	v_mul_f32_e32 v169, v66, v66
	v_pk_fma_f32 v[148:149], v[78:79], v[78:79], v[160:161] op_sel_hi:[1,1,0]
	v_pk_fma_f32 v[150:151], v[80:81], v[80:81], v[162:163] op_sel_hi:[1,1,0]
	v_pk_add_f32 v[144:145], v[144:145], v[144:145] op_sel:[0,1] op_sel_hi:[1,0]
	v_pk_add_f32 v[134:135], v[134:135], v[134:135] op_sel:[0,1] op_sel_hi:[1,0]
	v_add_f32_e32 v129, v130, v131
	v_mov_b32_e32 v149, v164
	v_mov_b32_e32 v151, v165
	v_mov_b32_e32 v145, v168
	v_mov_b32_e32 v135, v169
	ds_bpermute_b32 v136, v121, v129
	v_pk_add_f32 v[132:133], v[148:149], v[150:151]
	v_pk_add_f32 v[130:131], v[134:135], v[144:145]
	s_waitcnt lgkmcnt(0)
	v_add_f32_e32 v129, v129, v136
	v_pk_add_f32 v[130:131], v[130:131], v[132:133]
	ds_bpermute_b32 v132, v122, v129
	v_add_f32_e32 v130, v130, v131
	ds_bpermute_b32 v131, v121, v130
	s_waitcnt lgkmcnt(1)
	v_add_f32_e32 v129, v129, v132
	ds_bpermute_b32 v132, v123, v129
	s_waitcnt lgkmcnt(1)
	v_add_f32_e32 v130, v130, v131
	ds_bpermute_b32 v131, v122, v130
	s_waitcnt lgkmcnt(1)
	v_add_f32_e32 v129, v129, v132
	ds_bpermute_b32 v132, v124, v129
	s_waitcnt lgkmcnt(1)
	v_add_f32_e32 v130, v130, v131
	ds_bpermute_b32 v131, v123, v130
	s_waitcnt lgkmcnt(1)
	v_add_f32_e32 v129, v129, v132
	ds_bpermute_b32 v132, v125, v129
	s_waitcnt lgkmcnt(1)
	v_add_f32_e32 v130, v130, v131
	ds_bpermute_b32 v131, v124, v130
	s_waitcnt lgkmcnt(1)
	v_add_f32_e32 v129, v129, v132
	ds_bpermute_b32 v132, v126, v129
	s_waitcnt lgkmcnt(1)
	v_add_f32_e32 v130, v130, v131
	ds_bpermute_b32 v131, v125, v130
	s_waitcnt lgkmcnt(1)
	v_add_f32_e32 v129, v129, v132
	v_fmamk_f32 v129, v129, 0x3a000000, v127
	s_waitcnt lgkmcnt(0)
	v_add_f32_e32 v130, v130, v131
	ds_bpermute_b32 v131, v126, v130
	v_mul_f32_e32 v132, 0x4f800000, v129
	v_cmp_gt_f32_e32 vcc, s25, v129
	s_waitcnt lgkmcnt(0)
	v_add_f32_e32 v130, v130, v131
	v_cndmask_b32_e32 v129, v129, v132, vcc
	v_sqrt_f32_e32 v131, v129
	v_fmamk_f32 v130, v130, 0x3a000000, v127
	v_mul_f32_e32 v132, 0x4f800000, v130
	v_cmp_gt_f32_e64 s[4:5], s25, v130
	v_add_u32_e32 v133, -1, v131
	v_add_u32_e32 v134, 1, v131
	v_cndmask_b32_e64 v130, v130, v132, s[4:5]
	v_sqrt_f32_e32 v132, v130
	v_fma_f32 v135, -v133, v131, v129
	v_fma_f32 v136, -v134, v131, v129
	v_cmp_ge_f32_e64 s[6:7], 0, v135
	s_nop 1
	v_cndmask_b32_e64 v131, v131, v133, s[6:7]
	v_cmp_lt_f32_e64 s[6:7], 0, v136
	v_add_u32_e32 v133, -1, v132
	v_fma_f32 v136, -v133, v132, v130
	v_cndmask_b32_e64 v131, v131, v134, s[6:7]
	v_add_u32_e32 v134, 1, v132
	v_mul_f32_e32 v135, 0x37800000, v131
	v_fma_f32 v137, -v134, v132, v130
	v_cndmask_b32_e32 v131, v131, v135, vcc
	v_cmp_ge_f32_e32 vcc, 0, v136
	v_cmp_class_f32_e64 s[6:7], v129, v128
	s_nop 0
	v_cndmask_b32_e32 v132, v132, v133, vcc
	v_cmp_lt_f32_e32 vcc, 0, v137
	v_cndmask_b32_e64 v129, v131, v129, s[6:7]
	s_nop 0
	v_cndmask_b32_e32 v131, v132, v134, vcc
	v_div_scale_f32 v132, s[6:7], v129, v129, 1.0
	v_mul_f32_e32 v134, 0x37800000, v131
	v_rcp_f32_e32 v135, v132
	v_cndmask_b32_e64 v131, v131, v134, s[4:5]
	v_cmp_class_f32_e64 s[4:5], v130, v128
	v_div_scale_f32 v133, vcc, 1.0, v129, 1.0
	s_nop 0
	v_cndmask_b32_e64 v131, v131, v130, s[4:5]
	v_div_scale_f32 v134, s[4:5], v131, v131, 1.0
	v_rcp_f32_e32 v137, v134
	v_fma_f32 v130, -v132, v135, 1.0
	v_fmac_f32_e32 v135, v130, v135
	v_mul_f32_e32 v130, v133, v135
	v_fma_f32 v138, -v132, v130, v133
	v_fma_f32 v139, -v134, v137, 1.0
	v_div_scale_f32 v136, s[4:5], 1.0, v131, 1.0
	v_fmac_f32_e32 v130, v138, v135
	v_fmac_f32_e32 v137, v139, v137
	v_fma_f32 v132, -v132, v130, v133
	v_mul_f32_e32 v133, v136, v137
	v_div_fmas_f32 v130, v132, v135, v130
	v_fma_f32 v132, -v134, v133, v136
	v_fmac_f32_e32 v133, v132, v137
	v_div_fixup_f32 v130, v130, v129, 1.0
	v_fma_f32 v129, -v134, v133, v136
	s_mov_b64 vcc, s[4:5]
	v_pk_mul_f32 v[2:3], v[2:3], v[130:131] op_sel_hi:[1,0]
	v_pk_mul_f32 v[4:5], v[4:5], v[130:131] op_sel_hi:[1,0]
	v_pk_mul_f32 v[6:7], v[6:7], v[130:131] op_sel_hi:[1,0]
	v_pk_mul_f32 v[10:11], v[10:11], v[130:131] op_sel_hi:[1,0]
	v_pk_mul_f32 v[18:19], v[18:19], v[130:131] op_sel_hi:[1,0]
	v_pk_mul_f32 v[20:21], v[20:21], v[130:131] op_sel_hi:[1,0]
	v_div_fmas_f32 v129, v129, v137, v133
	v_pk_mul_f32 v[8:9], v[8:9], v[130:131] op_sel_hi:[1,0]
	v_pk_mul_f32 v[12:13], v[12:13], v[130:131] op_sel_hi:[1,0]
	v_pk_mul_f32 v[22:23], v[22:23], v[130:131] op_sel_hi:[1,0]
	v_pk_mul_f32 v[24:25], v[24:25], v[130:131] op_sel_hi:[1,0]
	v_pk_mul_f32 v[14:15], v[14:15], v[130:131] op_sel_hi:[1,0]
	v_pk_mul_f32 v[16:17], v[16:17], v[130:131] op_sel_hi:[1,0]
	v_pk_mul_f32 v[26:27], v[26:27], v[130:131] op_sel_hi:[1,0]
	v_pk_mul_f32 v[28:29], v[28:29], v[130:131] op_sel_hi:[1,0]
	v_pk_mul_f32 v[30:31], v[30:31], v[130:131] op_sel_hi:[1,0]
	v_pk_mul_f32 v[32:33], v[32:33], v[130:131] op_sel_hi:[1,0]
	v_pk_mul_f32 v[2:3], v[38:39], v[2:3]
	v_pk_mul_f32 v[4:5], v[40:41], v[4:5]
	v_pk_mul_f32 v[6:7], v[34:35], v[6:7]
	v_pk_mul_f32 v[10:11], v[46:47], v[10:11]
	v_pk_mul_f32 v[18:19], v[54:55], v[18:19]
	v_pk_mul_f32 v[20:21], v[56:57], v[20:21]
	v_div_fixup_f32 v130, v129, v131, 1.0
	v_pk_mul_f32 v[8:9], v[36:37], v[8:9]
	v_pk_mul_f32 v[12:13], v[48:49], v[12:13]
	v_pk_mul_f32 v[22:23], v[42:43], v[22:23]
	v_pk_mul_f32 v[24:25], v[44:45], v[24:25]
	v_pk_mul_f32 v[14:15], v[50:51], v[14:15]
	v_pk_mul_f32 v[16:17], v[52:53], v[16:17]
	v_pk_mul_f32 v[26:27], v[62:63], v[26:27]
	v_pk_mul_f32 v[28:29], v[64:65], v[28:29]
	v_pk_mul_f32 v[30:31], v[58:59], v[30:31]
	v_pk_mul_f32 v[32:33], v[60:61], v[32:33]
	v_cvt_pk_bf16_f32 v2, v2, v3
	v_cvt_pk_bf16_f32 v3, v4, v5
	v_cvt_pk_bf16_f32 v4, v6, v7
	v_cvt_pk_bf16_f32 v6, v10, v11
	v_cvt_pk_bf16_f32 v10, v18, v19
	v_cvt_pk_bf16_f32 v11, v20, v21
	v_pk_mul_f32 v[18:19], v[94:95], v[130:131] op_sel_hi:[1,0]
	v_pk_mul_f32 v[20:21], v[96:97], v[130:131] op_sel_hi:[1,0]
	v_cvt_pk_bf16_f32 v5, v8, v9
	v_cvt_pk_bf16_f32 v7, v12, v13
	v_cvt_pk_bf16_f32 v8, v22, v23
	v_cvt_pk_bf16_f32 v9, v24, v25
	v_cvt_pk_bf16_f32 v12, v14, v15
	v_cvt_pk_bf16_f32 v13, v16, v17
	v_cvt_pk_bf16_f32 v14, v26, v27
	v_cvt_pk_bf16_f32 v15, v28, v29
	v_cvt_pk_bf16_f32 v16, v30, v31
	v_cvt_pk_bf16_f32 v17, v32, v33
	v_pk_mul_f32 v[22:23], v[90:91], v[130:131] op_sel_hi:[1,0]
	v_pk_mul_f32 v[24:25], v[92:93], v[130:131] op_sel_hi:[1,0]
	v_pk_mul_f32 v[26:27], v[70:71], v[130:131] op_sel_hi:[1,0]
	v_pk_mul_f32 v[28:29], v[72:73], v[130:131] op_sel_hi:[1,0]
	v_pk_mul_f32 v[30:31], v[82:83], v[130:131] op_sel_hi:[1,0]
	v_pk_mul_f32 v[32:33], v[84:85], v[130:131] op_sel_hi:[1,0]
	v_pk_mul_f32 v[70:71], v[86:87], v[130:131] op_sel_hi:[1,0]
	v_pk_mul_f32 v[72:73], v[88:89], v[130:131] op_sel_hi:[1,0]
	v_pk_mul_f32 v[74:75], v[74:75], v[130:131] op_sel_hi:[1,0]
	v_pk_mul_f32 v[76:77], v[76:77], v[130:131] op_sel_hi:[1,0]
	v_pk_mul_f32 v[78:79], v[78:79], v[130:131] op_sel_hi:[1,0]
	v_pk_mul_f32 v[80:81], v[80:81], v[130:131] op_sel_hi:[1,0]
	v_pk_mul_f32 v[66:67], v[66:67], v[130:131] op_sel_hi:[1,0]
	v_pk_mul_f32 v[68:69], v[68:69], v[130:131] op_sel_hi:[1,0]
	global_store_dwordx2 v[116:117], v[2:3], off sc1
	v_pk_mul_f32 v[2:3], v[38:39], v[18:19]
	v_pk_mul_f32 v[18:19], v[40:41], v[20:21]
	v_pk_mul_f32 v[20:21], v[34:35], v[22:23]
	v_pk_mul_f32 v[22:23], v[36:37], v[24:25]
	v_pk_mul_f32 v[24:25], v[46:47], v[26:27]
	v_pk_mul_f32 v[26:27], v[48:49], v[28:29]
	v_pk_mul_f32 v[28:29], v[42:43], v[30:31]
	v_pk_mul_f32 v[30:31], v[44:45], v[32:33]
	v_pk_mul_f32 v[32:33], v[54:55], v[70:71]
	v_pk_mul_f32 v[34:35], v[56:57], v[72:73]
	v_pk_mul_f32 v[36:37], v[50:51], v[74:75]
	v_pk_mul_f32 v[38:39], v[52:53], v[76:77]
	v_pk_mul_f32 v[40:41], v[62:63], v[78:79]
	v_pk_mul_f32 v[42:43], v[64:65], v[80:81]
	v_pk_mul_f32 v[44:45], v[58:59], v[66:67]
	v_pk_mul_f32 v[46:47], v[60:61], v[68:69]
	v_cvt_pk_bf16_f32 v2, v2, v3
	v_cvt_pk_bf16_f32 v3, v18, v19
	v_cvt_pk_bf16_f32 v18, v20, v21
	v_cvt_pk_bf16_f32 v19, v22, v23
	v_cvt_pk_bf16_f32 v20, v24, v25
	v_cvt_pk_bf16_f32 v21, v26, v27
	v_cvt_pk_bf16_f32 v22, v28, v29
	v_cvt_pk_bf16_f32 v23, v30, v31
	v_cvt_pk_bf16_f32 v24, v32, v33
	v_cvt_pk_bf16_f32 v25, v34, v35
	v_cvt_pk_bf16_f32 v26, v36, v37
	v_cvt_pk_bf16_f32 v27, v38, v39
	v_cvt_pk_bf16_f32 v28, v40, v41
	v_cvt_pk_bf16_f32 v29, v42, v43
	v_cvt_pk_bf16_f32 v30, v44, v45
	v_cvt_pk_bf16_f32 v31, v46, v47
	global_store_dwordx2 v[118:119], v[2:3], off sc1
	global_store_dwordx2 v[116:117], v[4:5], off offset:512 sc1
	global_store_dwordx2 v[118:119], v[18:19], off offset:512 sc1
	global_store_dwordx2 v[116:117], v[6:7], off offset:1024 sc1
	global_store_dwordx2 v[118:119], v[20:21], off offset:1024 sc1
	global_store_dwordx2 v[116:117], v[8:9], off offset:1536 sc1
	global_store_dwordx2 v[118:119], v[22:23], off offset:1536 sc1
	global_store_dwordx2 v[116:117], v[10:11], off offset:2048 sc1
	global_store_dwordx2 v[118:119], v[24:25], off offset:2048 sc1
	global_store_dwordx2 v[116:117], v[12:13], off offset:2560 sc1
	global_store_dwordx2 v[118:119], v[26:27], off offset:2560 sc1
	global_store_dwordx2 v[116:117], v[14:15], off offset:3072 sc1
	global_store_dwordx2 v[118:119], v[28:29], off offset:3072 sc1
	global_store_dwordx2 v[116:117], v[16:17], off offset:3584 sc1
	global_store_dwordx2 v[118:119], v[30:31], off offset:3584 sc1
	v_lshl_add_u64 v[116:117], v[116:117], 0, s[20:21]
	s_cbranch_scc1 .LBB0_79
	v_readlane_b32 s0, v254, 0
	s_add_i32 s0, s0, s26
	s_cmpk_gt_i32 s0, 0x3fff
	s_cbranch_scc1 .LBB0_77
.LBB0_81:
	s_ashr_i32 s1, s0, 31
	s_lshl_b64 s[4:5], s[0:1], 13
	s_add_u32 s4, s16, s4
	s_addc_u32 s5, s17, s5
	v_lshlrev_b64 v[34:35], 4, v[98:99]
	v_lshl_add_u64 v[2:3], s[4:5], 0, v[34:35]
	global_load_dwordx4 v[30:33], v[2:3], off
	global_load_dwordx4 v[22:25], v[2:3], off offset:1024
	global_load_dwordx4 v[26:29], v[2:3], off offset:2048
	global_load_dwordx4 v[10:13], v[2:3], off offset:3072
	s_movk_i32 s3, 0x1000
	v_add_co_u32_e32 v36, vcc, s3, v2
	v_xor_b32_e32 v61, 4, v120
	s_nop 0
	v_addc_co_u32_e32 v37, vcc, 0, v3, vcc
	global_load_dwordx4 v[6:9], v[36:37], off
	global_load_dwordx4 v[18:21], v[36:37], off offset:1024
	global_load_dwordx4 v[2:5], v[36:37], off offset:3072
	global_load_dwordx4 v[14:17], v[36:37], off offset:2048
	s_load_dwordx2 s[4:5], s[12:13], 0x18
	s_lshl_b64 s[0:1], s[0:1], 12
	s_add_u32 s0, s14, s0
	s_addc_u32 s1, s15, s1
	s_waitcnt lgkmcnt(0)
	v_lshl_add_u64 v[38:39], s[4:5], 0, v[34:35]
	global_load_dwordx4 v[34:37], v[38:39], off
	s_mov_b32 s4, 0xf800000
	s_waitcnt vmcnt(8)
	v_mov_b32_e32 v42, v31
	s_waitcnt vmcnt(7)
	v_mov_b32_e32 v43, v23
	v_mov_b32_e32 v46, v33
	v_mov_b32_e32 v47, v25
	v_mov_b32_e32 v40, v30
	v_mov_b32_e32 v41, v22
	v_mov_b32_e32 v44, v32
	v_mov_b32_e32 v45, v24
	s_waitcnt vmcnt(6)
	v_pk_mul_f32 v[48:49], v[28:29], v[28:29]
	v_pk_mul_f32 v[50:51], v[26:27], v[26:27]
	v_pk_mul_f32 v[42:43], v[42:43], v[42:43]
	v_pk_mul_f32 v[46:47], v[46:47], v[46:47]
	v_pk_mov_b32 v[56:57], v[50:51], v[48:49] op_sel:[1,0]
	v_mov_b32_e32 v51, v49
	v_pk_fma_f32 v[40:41], v[40:41], v[40:41], v[42:43]
	v_pk_fma_f32 v[42:43], v[44:45], v[44:45], v[46:47]
	s_waitcnt vmcnt(5)
	v_mul_f32_e32 v52, v11, v11
	v_mul_f32_e32 v54, v13, v13
	v_pk_add_f32 v[44:45], v[56:57], v[50:51]
	v_pk_add_f32 v[40:41], v[40:41], v[42:43]
	s_waitcnt vmcnt(4)
	v_mul_f32_e32 v63, v6, v6
	v_mul_f32_e32 v64, v7, v7
	v_mul_f32_e32 v65, v8, v8
	v_mul_f32_e32 v66, v9, v9
	v_pk_fma_f32 v[48:49], v[10:11], v[10:11], v[52:53] op_sel_hi:[1,1,0]
	v_pk_fma_f32 v[52:53], v[12:13], v[12:13], v[54:55] op_sel_hi:[1,1,0]
	v_pk_add_f32 v[42:43], v[44:45], v[44:45] op_sel:[0,1] op_sel_hi:[1,0]
	v_pk_add_f32 v[40:41], v[40:41], v[40:41] op_sel:[0,1] op_sel_hi:[1,0]
	s_waitcnt vmcnt(3)
	v_pk_mul_f32 v[54:55], v[20:21], v[20:21]
	v_pk_mul_f32 v[58:59], v[18:19], v[18:19]
	v_mov_b32_e32 v49, v65
	v_mov_b32_e32 v53, v66
	v_mov_b32_e32 v43, v64
	v_mov_b32_e32 v41, v63
	v_pk_mov_b32 v[46:47], v[58:59], v[54:55] op_sel:[1,0]
	v_mov_b32_e32 v59, v55
	v_pk_add_f32 v[44:45], v[48:49], v[52:53]
	v_pk_add_f32 v[40:41], v[40:41], v[42:43]
	s_waitcnt vmcnt(1)
	v_mul_f32_e32 v60, v15, v15
	v_mul_f32_e32 v62, v17, v17
	v_pk_add_f32 v[46:47], v[46:47], v[58:59]
	v_pk_add_f32 v[40:41], v[40:41], v[44:45]
	v_mul_f32_e32 v67, v2, v2
	v_mul_f32_e32 v68, v3, v3
	v_mul_f32_e32 v69, v4, v4
	v_mul_f32_e32 v70, v5, v5
	v_pk_fma_f32 v[50:51], v[14:15], v[14:15], v[60:61] op_sel_hi:[1,1,0]
	v_pk_fma_f32 v[54:55], v[16:17], v[16:17], v[62:63] op_sel_hi:[1,1,0]
	v_pk_add_f32 v[46:47], v[46:47], v[46:47] op_sel:[0,1] op_sel_hi:[1,0]
	v_pk_add_f32 v[40:41], v[40:41], v[40:41] op_sel:[0,1] op_sel_hi:[1,0]
	v_mov_b32_e32 v51, v69
	v_mov_b32_e32 v55, v70
	v_mov_b32_e32 v47, v68
	v_mov_b32_e32 v41, v67
	v_pk_add_f32 v[48:49], v[50:51], v[54:55]
	v_pk_add_f32 v[40:41], v[40:41], v[46:47]
	v_xor_b32_e32 v42, 8, v120
	v_pk_add_f32 v[40:41], v[40:41], v[48:49]
	v_mov_b32_e32 v43, 0x260
	v_add_f32_e32 v40, v40, v41
	ds_bpermute_b32 v41, v61, v40
	s_waitcnt lgkmcnt(0)
	v_add_f32_e32 v40, v40, v41
	ds_bpermute_b32 v41, v42, v40
	v_xor_b32_e32 v42, 16, v120
	s_waitcnt lgkmcnt(0)
	v_add_f32_e32 v40, v40, v41
	ds_bpermute_b32 v41, v42, v40
	v_xor_b32_e32 v42, 32, v120
	s_waitcnt lgkmcnt(0)
	v_add_f32_e32 v40, v40, v41
	ds_bpermute_b32 v41, v42, v40
	v_xor_b32_e32 v42, 64, v120
	s_waitcnt lgkmcnt(0)
	v_add_f32_e32 v40, v40, v41
	ds_bpermute_b32 v41, v42, v40
	v_xor_b32_e32 v42, 0x80, v120
	s_waitcnt lgkmcnt(0)
	v_add_f32_e32 v40, v40, v41
	ds_bpermute_b32 v41, v42, v40
	v_mov_b32_e32 v42, 0x358637bd
	s_waitcnt lgkmcnt(0)
	v_add_f32_e32 v40, v40, v41
	v_fmac_f32_e32 v42, 0x3a000000, v40
	v_mul_f32_e32 v40, 0x4f800000, v42
	v_cmp_gt_f32_e32 vcc, s4, v42
	s_nop 1
	v_cndmask_b32_e32 v40, v42, v40, vcc
	v_sqrt_f32_e32 v41, v40
	s_nop 0
	v_add_u32_e32 v42, -1, v41
	v_add_u32_e32 v44, 1, v41
	v_fma_f32 v45, -v42, v41, v40
	v_fma_f32 v46, -v44, v41, v40
	v_cmp_ge_f32_e64 s[4:5], 0, v45
	s_nop 1
	v_cndmask_b32_e64 v41, v41, v42, s[4:5]
	v_cmp_lt_f32_e64 s[4:5], 0, v46
	s_nop 1
	v_cndmask_b32_e64 v41, v41, v44, s[4:5]
	v_mul_f32_e32 v42, 0x37800000, v41
	v_cndmask_b32_e32 v41, v41, v42, vcc
	v_cmp_class_f32_e32 vcc, v40, v43
	s_nop 1
	v_cndmask_b32_e32 v42, v41, v40, vcc
	v_div_scale_f32 v43, s[4:5], v42, v42, 1.0
	v_rcp_f32_e32 v44, v43
	v_div_scale_f32 v45, vcc, 1.0, v42, 1.0
	v_lshl_add_u64 v[40:41], v[98:99], 3, s[0:1]
	v_fma_f32 v46, -v43, v44, 1.0
	v_fmac_f32_e32 v44, v46, v44
	v_mul_f32_e32 v46, v45, v44
	v_fma_f32 v47, -v43, v46, v45
	v_fmac_f32_e32 v46, v47, v44
	v_fma_f32 v43, -v43, v46, v45
	v_div_fmas_f32 v43, v43, v44, v46
	v_div_fixup_f32 v42, v43, v42, 1.0
	v_pk_mul_f32 v[30:31], v[30:31], v[42:43] op_sel_hi:[1,0]
	v_pk_mul_f32 v[32:33], v[32:33], v[42:43] op_sel_hi:[1,0]
	s_waitcnt vmcnt(0)
	v_pk_mul_f32 v[30:31], v[34:35], v[30:31]
	v_pk_mul_f32 v[32:33], v[36:37], v[32:33]
	v_cvt_pk_bf16_f32 v30, v30, v31
	v_cvt_pk_bf16_f32 v31, v32, v33
	global_store_dwordx2 v[40:41], v[30:31], off sc1
	global_load_dwordx4 v[30:33], v[38:39], off offset:1024
	v_pk_mul_f32 v[22:23], v[22:23], v[42:43] op_sel_hi:[1,0]
	v_pk_mul_f32 v[24:25], v[24:25], v[42:43] op_sel_hi:[1,0]
	v_pk_mul_f32 v[26:27], v[26:27], v[42:43] op_sel_hi:[1,0]
	v_pk_mul_f32 v[28:29], v[28:29], v[42:43] op_sel_hi:[1,0]
	v_pk_mul_f32 v[10:11], v[10:11], v[42:43] op_sel_hi:[1,0]
	v_pk_mul_f32 v[12:13], v[12:13], v[42:43] op_sel_hi:[1,0]
	v_pk_mul_f32 v[6:7], v[6:7], v[42:43] op_sel_hi:[1,0]
	v_pk_mul_f32 v[8:9], v[8:9], v[42:43] op_sel_hi:[1,0]
	v_pk_mul_f32 v[2:3], v[2:3], v[42:43] op_sel_hi:[1,0]
	v_pk_mul_f32 v[4:5], v[4:5], v[42:43] op_sel_hi:[1,0]
	s_waitcnt vmcnt(0)
	v_pk_mul_f32 v[22:23], v[30:31], v[22:23]
	v_pk_mul_f32 v[24:25], v[32:33], v[24:25]
	v_cvt_pk_bf16_f32 v22, v22, v23
	v_cvt_pk_bf16_f32 v23, v24, v25
	global_store_dwordx2 v[40:41], v[22:23], off offset:512 sc1
	global_load_dwordx4 v[22:25], v[38:39], off offset:2048
	s_waitcnt vmcnt(0)
	v_pk_mul_f32 v[22:23], v[22:23], v[26:27]
	v_pk_mul_f32 v[24:25], v[24:25], v[28:29]
	v_cvt_pk_bf16_f32 v22, v22, v23
	v_cvt_pk_bf16_f32 v23, v24, v25
	global_store_dwordx2 v[40:41], v[22:23], off offset:1024 sc1
	global_load_dwordx4 v[22:25], v[38:39], off offset:3072
	v_add_co_u32_e32 v26, vcc, s3, v38
	s_waitcnt vmcnt(0)
	v_pk_mul_f32 v[10:11], v[22:23], v[10:11]
	v_pk_mul_f32 v[12:13], v[24:25], v[12:13]
	v_cvt_pk_bf16_f32 v10, v10, v11
	v_cvt_pk_bf16_f32 v11, v12, v13
	v_addc_co_u32_e32 v27, vcc, 0, v39, vcc
	global_store_dwordx2 v[40:41], v[10:11], off offset:1536 sc1
	global_load_dwordx4 v[10:13], v[26:27], off
	s_waitcnt vmcnt(0)
	v_pk_mul_f32 v[6:7], v[6:7], v[10:11]
	v_pk_mul_f32 v[8:9], v[8:9], v[12:13]
	v_cvt_pk_bf16_f32 v6, v6, v7
	v_cvt_pk_bf16_f32 v7, v8, v9
	global_store_dwordx2 v[40:41], v[6:7], off offset:2048 sc1
	global_load_dwordx4 v[6:9], v[26:27], off offset:1024
	v_pk_mul_f32 v[10:11], v[18:19], v[42:43] op_sel_hi:[1,0]
	v_pk_mul_f32 v[12:13], v[20:21], v[42:43] op_sel_hi:[1,0]
	s_waitcnt vmcnt(0)
	v_pk_mul_f32 v[6:7], v[10:11], v[6:7]
	v_pk_mul_f32 v[8:9], v[12:13], v[8:9]
	v_cvt_pk_bf16_f32 v6, v6, v7
	v_cvt_pk_bf16_f32 v7, v8, v9
	global_store_dwordx2 v[40:41], v[6:7], off offset:2560 sc1
	global_load_dwordx4 v[6:9], v[26:27], off offset:2048
	v_pk_mul_f32 v[10:11], v[14:15], v[42:43] op_sel_hi:[1,0]
	v_pk_mul_f32 v[12:13], v[16:17], v[42:43] op_sel_hi:[1,0]
	s_waitcnt vmcnt(0)
	v_pk_mul_f32 v[6:7], v[10:11], v[6:7]
	v_pk_mul_f32 v[8:9], v[12:13], v[8:9]
	v_cvt_pk_bf16_f32 v6, v6, v7
	v_cvt_pk_bf16_f32 v7, v8, v9
	global_store_dwordx2 v[40:41], v[6:7], off offset:3072 sc1
	global_load_dwordx4 v[6:9], v[26:27], off offset:3072
	s_waitcnt vmcnt(0)
	v_pk_mul_f32 v[2:3], v[2:3], v[6:7]
	v_pk_mul_f32 v[4:5], v[4:5], v[8:9]
	v_cvt_pk_bf16_f32 v2, v2, v3
	v_cvt_pk_bf16_f32 v3, v4, v5
	global_store_dwordx2 v[40:41], v[2:3], off offset:3584 sc1
	s_cmpk_gt_i32 s84, 0x7ff
	s_cbranch_scc1 .LBB0_84

.LBB0_83:
	s_and_b32 s6, s11, 0x1ff800
	s_lshl_b32 s6, s6, 2
	v_lshl_add_u64 v[32:33], v[2:3], 0, s[6:7]
	global_load_dwordx4 v[16:19], v[32:33], off
	global_load_dwordx4 v[20:23], v[32:33], off offset:1024
	global_load_dwordx4 v[24:27], v[32:33], off offset:2048
	global_load_dwordx4 v[28:31], v[32:33], off offset:3072
	s_and_b32 s4, s3, 0xfffff800
	s_ashr_i32 s5, s4, 31
	v_lshl_add_u64 v[52:53], s[4:5], 2, v[4:5]
	v_add_co_u32_e32 v54, vcc, s13, v32
	s_add_i32 s15, s15, s86
	s_nop 0
	v_addc_co_u32_e32 v55, vcc, 0, v33, vcc
	global_load_dwordx4 v[32:35], v[52:53], off
	global_load_dwordx4 v[36:39], v[54:55], off
	global_load_dwordx4 v[40:43], v[54:55], off offset:1024
	global_load_dwordx4 v[44:47], v[54:55], off offset:3072
	global_load_dwordx4 v[48:51], v[54:55], off offset:2048
	s_add_i32 s3, s3, s10
	s_add_i32 s11, s11, s12
	s_cmpk_lt_i32 s15, 0x800
	s_waitcnt vmcnt(8)
	v_mov_b32_e32 v56, v17
	s_waitcnt vmcnt(7)
	v_mov_b32_e32 v57, v21
	v_mov_b32_e32 v60, v19
	v_mov_b32_e32 v61, v23
	v_mov_b32_e32 v54, v16
	v_mov_b32_e32 v55, v20
	v_mov_b32_e32 v58, v18
	v_mov_b32_e32 v59, v22
	s_waitcnt vmcnt(6)
	v_pk_mul_f32 v[62:63], v[26:27], v[26:27]
	v_pk_mul_f32 v[64:65], v[24:25], v[24:25]
	v_pk_mul_f32 v[56:57], v[56:57], v[56:57]
	v_pk_mul_f32 v[60:61], v[60:61], v[60:61]
	v_pk_mov_b32 v[70:71], v[64:65], v[62:63] op_sel:[1,0]
	v_mov_b32_e32 v65, v63
	v_pk_fma_f32 v[54:55], v[54:55], v[54:55], v[56:57]
	v_pk_fma_f32 v[56:57], v[58:59], v[58:59], v[60:61]
	s_waitcnt vmcnt(5)
	v_mul_f32_e32 v66, v29, v29
	v_mul_f32_e32 v68, v31, v31
	v_pk_add_f32 v[58:59], v[70:71], v[64:65]
	v_pk_add_f32 v[54:55], v[54:55], v[56:57]
	s_waitcnt vmcnt(3)
	v_mul_f32_e32 v75, v36, v36
	v_mul_f32_e32 v77, v37, v37
	v_mul_f32_e32 v78, v38, v38
	v_mul_f32_e32 v79, v39, v39
	v_pk_fma_f32 v[62:63], v[28:29], v[28:29], v[66:67] op_sel_hi:[1,1,0]
	v_pk_fma_f32 v[66:67], v[30:31], v[30:31], v[68:69] op_sel_hi:[1,1,0]
	v_pk_add_f32 v[56:57], v[58:59], v[58:59] op_sel:[0,1] op_sel_hi:[1,0]
	v_pk_add_f32 v[54:55], v[54:55], v[54:55] op_sel:[0,1] op_sel_hi:[1,0]
	s_waitcnt vmcnt(2)
	v_pk_mul_f32 v[68:69], v[42:43], v[42:43]
	v_pk_mul_f32 v[72:73], v[40:41], v[40:41]
	v_mov_b32_e32 v63, v78
	v_mov_b32_e32 v67, v79
	v_mov_b32_e32 v57, v77
	v_mov_b32_e32 v55, v75
	v_pk_mov_b32 v[60:61], v[72:73], v[68:69] op_sel:[1,0]
	v_mov_b32_e32 v73, v69
	v_pk_add_f32 v[58:59], v[62:63], v[66:67]
	v_pk_add_f32 v[54:55], v[54:55], v[56:57]
	s_waitcnt vmcnt(0)
	v_mul_f32_e32 v74, v49, v49
	v_mul_f32_e32 v76, v51, v51
	v_pk_add_f32 v[60:61], v[60:61], v[72:73]
	v_pk_add_f32 v[54:55], v[54:55], v[58:59]
	v_mul_f32_e32 v80, v44, v44
	v_mul_f32_e32 v81, v45, v45
	v_mul_f32_e32 v82, v46, v46
	v_mul_f32_e32 v83, v47, v47
	v_pk_fma_f32 v[64:65], v[48:49], v[48:49], v[74:75] op_sel_hi:[1,1,0]
	v_pk_fma_f32 v[68:69], v[50:51], v[50:51], v[76:77] op_sel_hi:[1,1,0]
	v_pk_add_f32 v[60:61], v[60:61], v[60:61] op_sel:[0,1] op_sel_hi:[1,0]
	v_pk_add_f32 v[54:55], v[54:55], v[54:55] op_sel:[0,1] op_sel_hi:[1,0]
	v_mov_b32_e32 v65, v82
	v_mov_b32_e32 v69, v83
	v_mov_b32_e32 v61, v81
	v_mov_b32_e32 v55, v80
	v_pk_add_f32 v[62:63], v[64:65], v[68:69]
	v_pk_add_f32 v[54:55], v[54:55], v[60:61]
	s_nop 0
	v_pk_add_f32 v[54:55], v[54:55], v[62:63]
	s_nop 0
	v_add_f32_e32 v54, v54, v55
	ds_bpermute_b32 v55, v8, v54
	s_waitcnt lgkmcnt(0)
	v_add_f32_e32 v54, v54, v55
	ds_bpermute_b32 v55, v9, v54
	s_waitcnt lgkmcnt(0)
	v_add_f32_e32 v54, v54, v55
	ds_bpermute_b32 v55, v10, v54
	s_waitcnt lgkmcnt(0)
	v_add_f32_e32 v54, v54, v55
	ds_bpermute_b32 v55, v11, v54
	s_waitcnt lgkmcnt(0)
	v_add_f32_e32 v54, v54, v55
	ds_bpermute_b32 v55, v12, v54
	s_waitcnt lgkmcnt(0)
	v_add_f32_e32 v54, v54, v55
	ds_bpermute_b32 v55, v13, v54
	s_waitcnt lgkmcnt(0)
	v_add_f32_e32 v54, v54, v55
	v_fmamk_f32 v54, v54, 0x3a000000, v14
	v_mul_f32_e32 v55, 0x4f800000, v54
	v_cmp_gt_f32_e32 vcc, s14, v54
	s_nop 1
	v_cndmask_b32_e32 v54, v54, v55, vcc
	v_sqrt_f32_e32 v55, v54
	s_nop 0
	v_add_u32_e32 v56, -1, v55
	v_add_u32_e32 v57, 1, v55
	v_fma_f32 v58, -v56, v55, v54
	v_fma_f32 v59, -v57, v55, v54
	v_cmp_ge_f32_e64 s[4:5], 0, v58
	s_nop 1
	v_cndmask_b32_e64 v55, v55, v56, s[4:5]
	v_cmp_lt_f32_e64 s[4:5], 0, v59
	s_nop 1
	v_cndmask_b32_e64 v55, v55, v57, s[4:5]
	v_mul_f32_e32 v56, 0x37800000, v55
	v_cndmask_b32_e32 v55, v55, v56, vcc
	v_cmp_class_f32_e32 vcc, v54, v15
	s_nop 1
	v_cndmask_b32_e32 v54, v55, v54, vcc
	v_div_scale_f32 v55, s[4:5], v54, v54, 1.0
	v_rcp_f32_e32 v57, v55
	v_div_scale_f32 v56, vcc, 1.0, v54, 1.0
	v_fma_f32 v58, -v55, v57, 1.0
	v_fmac_f32_e32 v57, v58, v57
	v_mul_f32_e32 v58, v56, v57
	v_fma_f32 v59, -v55, v58, v56
	v_fmac_f32_e32 v58, v59, v57
	v_fma_f32 v55, -v55, v58, v56
	v_div_fmas_f32 v55, v55, v57, v58
	v_div_fixup_f32 v54, v55, v54, 1.0
	v_pk_mul_f32 v[16:17], v[16:17], v[54:55] op_sel_hi:[1,0]
	v_pk_mul_f32 v[18:19], v[18:19], v[54:55] op_sel_hi:[1,0]
	v_pk_mul_f32 v[16:17], v[32:33], v[16:17]
	v_pk_mul_f32 v[18:19], v[34:35], v[18:19]
	v_cvt_pk_bf16_f32 v16, v16, v17
	v_cvt_pk_bf16_f32 v17, v18, v19
	global_store_dwordx2 v[6:7], v[16:17], off sc1
	global_load_dwordx4 v[16:19], v[52:53], off offset:1024
	v_pk_mul_f32 v[20:21], v[20:21], v[54:55] op_sel_hi:[1,0]
	v_pk_mul_f32 v[22:23], v[22:23], v[54:55] op_sel_hi:[1,0]
	s_waitcnt vmcnt(0)
	v_pk_mul_f32 v[16:17], v[16:17], v[20:21]
	v_pk_mul_f32 v[18:19], v[18:19], v[22:23]
	v_cvt_pk_bf16_f32 v16, v16, v17
	v_cvt_pk_bf16_f32 v17, v18, v19
	global_store_dwordx2 v[6:7], v[16:17], off offset:512 sc1
	global_load_dwordx4 v[16:19], v[52:53], off offset:2048
	v_pk_mul_f32 v[20:21], v[24:25], v[54:55] op_sel_hi:[1,0]
	v_pk_mul_f32 v[22:23], v[26:27], v[54:55] op_sel_hi:[1,0]
	v_pk_mul_f32 v[24:25], v[30:31], v[54:55] op_sel_hi:[1,0]
	s_waitcnt vmcnt(0)
	v_pk_mul_f32 v[16:17], v[16:17], v[20:21]
	v_pk_mul_f32 v[18:19], v[18:19], v[22:23]
	v_cvt_pk_bf16_f32 v16, v16, v17
	v_cvt_pk_bf16_f32 v17, v18, v19
	global_store_dwordx2 v[6:7], v[16:17], off offset:1024 sc1
	global_load_dwordx4 v[16:19], v[52:53], off offset:3072
	v_pk_mul_f32 v[22:23], v[28:29], v[54:55] op_sel_hi:[1,0]
	v_add_co_u32_e32 v20, vcc, s13, v52
	s_waitcnt vmcnt(0)
	v_pk_mul_f32 v[16:17], v[16:17], v[22:23]
	v_pk_mul_f32 v[18:19], v[18:19], v[24:25]
	v_cvt_pk_bf16_f32 v16, v16, v17
	v_cvt_pk_bf16_f32 v17, v18, v19
	v_addc_co_u32_e32 v21, vcc, 0, v53, vcc
	global_store_dwordx2 v[6:7], v[16:17], off offset:1536 sc1
	global_load_dwordx4 v[16:19], v[20:21], off
	v_pk_mul_f32 v[22:23], v[36:37], v[54:55] op_sel_hi:[1,0]
	v_pk_mul_f32 v[24:25], v[38:39], v[54:55] op_sel_hi:[1,0]
	s_waitcnt vmcnt(0)
	v_pk_mul_f32 v[16:17], v[22:23], v[16:17]
	v_pk_mul_f32 v[18:19], v[24:25], v[18:19]
	v_cvt_pk_bf16_f32 v16, v16, v17
	v_cvt_pk_bf16_f32 v17, v18, v19
	global_store_dwordx2 v[6:7], v[16:17], off offset:2048 sc1
	global_load_dwordx4 v[16:19], v[20:21], off offset:1024
	v_pk_mul_f32 v[22:23], v[40:41], v[54:55] op_sel_hi:[1,0]
	v_pk_mul_f32 v[24:25], v[42:43], v[54:55] op_sel_hi:[1,0]
	s_waitcnt vmcnt(0)
	v_pk_mul_f32 v[16:17], v[22:23], v[16:17]
	v_pk_mul_f32 v[18:19], v[24:25], v[18:19]
	v_cvt_pk_bf16_f32 v16, v16, v17
	v_cvt_pk_bf16_f32 v17, v18, v19
	global_store_dwordx2 v[6:7], v[16:17], off offset:2560 sc1
	global_load_dwordx4 v[16:19], v[20:21], off offset:2048
	v_pk_mul_f32 v[22:23], v[48:49], v[54:55] op_sel_hi:[1,0]
	v_pk_mul_f32 v[24:25], v[50:51], v[54:55] op_sel_hi:[1,0]
	s_waitcnt vmcnt(0)
	v_pk_mul_f32 v[16:17], v[22:23], v[16:17]
	v_pk_mul_f32 v[18:19], v[24:25], v[18:19]
	v_cvt_pk_bf16_f32 v16, v16, v17
	v_cvt_pk_bf16_f32 v17, v18, v19
	global_store_dwordx2 v[6:7], v[16:17], off offset:3072 sc1
	global_load_dwordx4 v[16:19], v[20:21], off offset:3072
	v_pk_mul_f32 v[20:21], v[44:45], v[54:55] op_sel_hi:[1,0]
	v_pk_mul_f32 v[22:23], v[46:47], v[54:55] op_sel_hi:[1,0]
	s_waitcnt vmcnt(0)
	v_pk_mul_f32 v[16:17], v[20:21], v[16:17]
	v_pk_mul_f32 v[18:19], v[22:23], v[18:19]
	v_cvt_pk_bf16_f32 v16, v16, v17
	v_cvt_pk_bf16_f32 v17, v18, v19
	global_store_dwordx2 v[6:7], v[16:17], off offset:3584 sc1
	v_lshl_add_u64 v[6:7], v[6:7], 0, s[0:1]
	s_cbranch_scc1 .LBB0_83

.LBB0_644:
	s_ashr_i32 s15, s14, 31
	s_lshl_b64 s[4:5], s[14:15], 13
	v_lshl_add_u64 v[22:23], v[100:101], 0, s[4:5]
	global_load_dwordx4 v[82:85], v[114:115], off offset:-4096
	global_load_dwordx4 v[50:53], v[22:23], off
	global_load_dwordx4 v[54:57], v[104:105], off
	global_load_dwordx4 v[66:69], v[114:115], off offset:-3072
	global_load_dwordx4 v[38:41], v[22:23], off offset:1024
	global_load_dwordx4 v[42:45], v[104:105], off offset:1024
	global_load_dwordx4 v[58:61], v[114:115], off offset:-2048
	global_load_dwordx4 v[14:17], v[22:23], off offset:2048
	global_load_dwordx4 v[18:21], v[104:105], off offset:2048
	global_load_dwordx4 v[10:13], v[114:115], off offset:-1024
	global_load_dwordx4 v[2:5], v[22:23], off offset:3072
	global_load_dwordx4 v[6:9], v[104:105], off offset:3072
	global_load_dwordx4 v[46:49], v[114:115], off
	v_add_co_u32_e32 v70, vcc, s57, v22
	s_add_i32 s1, s1, s18
	s_nop 0
	v_addc_co_u32_e32 v71, vcc, 0, v23, vcc
	global_load_dwordx4 v[22:25], v[70:71], off
	global_load_dwordx4 v[26:29], v[106:107], off
	global_load_dwordx4 v[90:93], v[114:115], off offset:1024
	global_load_dwordx4 v[74:77], v[70:71], off offset:1024
	global_load_dwordx4 v[78:81], v[108:109], off
	global_load_dwordx4 v[62:65], v[114:115], off offset:2048
	global_load_dwordx4 v[30:33], v[70:71], off offset:2048
	global_load_dwordx4 v[34:37], v[110:111], off
	global_load_dwordx4 v[86:89], v[114:115], off offset:3072
	s_nop 0
	global_load_dwordx4 v[70:73], v[70:71], off offset:3072
	s_nop 0
	global_load_dwordx4 v[94:97], v[112:113], off
	s_add_i32 s0, s0, s18
	v_lshl_add_u64 v[114:115], v[114:115], 0, s[20:21]
	s_waitcnt vmcnt(23)
	v_mov_b32_e32 v126, v83
	v_mov_b32_e32 v124, v82
	v_mov_b32_e32 v128, v85
	s_waitcnt vmcnt(20)
	v_mov_b32_e32 v127, v67
	v_mov_b32_e32 v125, v66
	v_pk_mul_f32 v[126:127], v[126:127], v[126:127]
	v_mov_b32_e32 v129, v69
	v_pk_fma_f32 v[124:125], v[124:125], v[124:125], v[126:127]
	v_mov_b32_e32 v126, v84
	v_mov_b32_e32 v127, v68
	v_pk_mul_f32 v[128:129], v[128:129], v[128:129]
	v_mov_b32_e32 v130, v53
	v_pk_fma_f32 v[126:127], v[126:127], v[126:127], v[128:129]
	v_mov_b32_e32 v128, v51
	s_waitcnt vmcnt(19)
	v_mov_b32_e32 v129, v39
	v_pk_add_f32 v[124:125], v[124:125], v[126:127]
	v_mov_b32_e32 v126, v50
	v_mov_b32_e32 v127, v38
	v_pk_mul_f32 v[128:129], v[128:129], v[128:129]
	v_mov_b32_e32 v131, v41
	v_pk_fma_f32 v[126:127], v[126:127], v[126:127], v[128:129]
	v_mov_b32_e32 v128, v52
	v_mov_b32_e32 v129, v40
	v_pk_mul_f32 v[130:131], v[130:131], v[130:131]
	s_waitcnt vmcnt(11)
	v_mul_f32_e32 v123, v46, v46
	v_pk_fma_f32 v[128:129], v[128:129], v[128:129], v[130:131]
	v_pk_mul_f32 v[130:131], v[58:59], v[58:59]
	v_pk_add_f32 v[126:127], v[126:127], v[128:129]
	v_pk_mul_f32 v[128:129], v[60:61], v[60:61]
	v_pk_add_f32 v[124:125], v[124:125], v[124:125] op_sel:[0,1] op_sel_hi:[1,0]
	v_pk_mov_b32 v[132:133], v[130:131], v[128:129] op_sel:[1,0]
	v_mov_b32_e32 v131, v129
	v_pk_add_f32 v[128:129], v[132:133], v[130:131]
	v_pk_mul_f32 v[130:131], v[16:17], v[16:17]
	v_pk_mul_f32 v[132:133], v[14:15], v[14:15]
	v_pk_add_f32 v[128:129], v[128:129], v[128:129] op_sel:[0,1] op_sel_hi:[1,0]
	v_pk_mov_b32 v[134:135], v[132:133], v[130:131] op_sel:[1,0]
	v_mov_b32_e32 v133, v131
	v_pk_add_f32 v[130:131], v[134:135], v[132:133]
	v_mul_f32_e32 v132, v47, v47
	v_mov_b32_e32 v125, v123
	v_mov_b32_e32 v129, v132
	v_pk_add_f32 v[124:125], v[124:125], v[128:129]
	v_mul_f32_e32 v128, v11, v11
	v_mul_f32_e32 v133, v48, v48
	v_pk_fma_f32 v[128:129], v[10:11], v[10:11], v[128:129] op_sel_hi:[1,1,0]
	v_mul_f32_e32 v132, v13, v13
	v_mul_f32_e32 v134, v49, v49
	v_mov_b32_e32 v129, v133
	v_pk_fma_f32 v[132:133], v[12:13], v[12:13], v[132:133] op_sel_hi:[1,1,0]
	s_waitcnt vmcnt(10)
	v_mul_f32_e32 v123, v22, v22
	v_mov_b32_e32 v133, v134
	v_pk_add_f32 v[128:129], v[128:129], v[132:133]
	v_mul_f32_e32 v132, v23, v23
	v_pk_add_f32 v[124:125], v[124:125], v[128:129]
	v_pk_add_f32 v[126:127], v[126:127], v[126:127] op_sel:[0,1] op_sel_hi:[1,0]
	v_pk_add_f32 v[128:129], v[130:131], v[130:131] op_sel:[0,1] op_sel_hi:[1,0]
	v_mov_b32_e32 v127, v123
	v_mov_b32_e32 v129, v132
	v_pk_add_f32 v[126:127], v[126:127], v[128:129]
	v_mul_f32_e32 v128, v3, v3
	v_mul_f32_e32 v130, v5, v5
	v_mul_f32_e32 v133, v24, v24
	v_mul_f32_e32 v134, v25, v25
	v_pk_fma_f32 v[128:129], v[2:3], v[2:3], v[128:129] op_sel_hi:[1,1,0]
	v_pk_fma_f32 v[130:131], v[4:5], v[4:5], v[130:131] op_sel_hi:[1,1,0]
	v_mov_b32_e32 v129, v133
	v_mov_b32_e32 v131, v134
	v_pk_add_f32 v[128:129], v[128:129], v[130:131]
	s_waitcnt vmcnt(8)
	v_pk_mul_f32 v[130:131], v[90:91], v[90:91]
	v_pk_add_f32 v[126:127], v[126:127], v[128:129]
	v_pk_mul_f32 v[128:129], v[92:93], v[92:93]
	s_waitcnt vmcnt(2)
	v_mul_f32_e32 v123, v86, v86
	v_pk_mov_b32 v[132:133], v[130:131], v[128:129] op_sel:[1,0]
	v_mov_b32_e32 v131, v129
	v_pk_add_f32 v[128:129], v[132:133], v[130:131]
	v_pk_mul_f32 v[130:131], v[76:77], v[76:77]
	v_pk_mul_f32 v[132:133], v[74:75], v[74:75]
	v_pk_add_f32 v[124:125], v[124:125], v[124:125] op_sel:[0,1] op_sel_hi:[1,0]
	v_pk_mov_b32 v[134:135], v[132:133], v[130:131] op_sel:[1,0]
	v_mov_b32_e32 v133, v131
	v_pk_add_f32 v[130:131], v[134:135], v[132:133]
	v_mul_f32_e32 v132, v87, v87
	v_pk_add_f32 v[128:129], v[128:129], v[128:129] op_sel:[0,1] op_sel_hi:[1,0]
	v_mov_b32_e32 v125, v123
	v_mov_b32_e32 v129, v132
	v_pk_add_f32 v[124:125], v[124:125], v[128:129]
	v_mul_f32_e32 v128, v63, v63
	v_mul_f32_e32 v133, v88, v88
	v_pk_fma_f32 v[128:129], v[62:63], v[62:63], v[128:129] op_sel_hi:[1,1,0]
	v_mul_f32_e32 v132, v65, v65
	v_mul_f32_e32 v134, v89, v89
	v_mov_b32_e32 v129, v133
	v_pk_fma_f32 v[132:133], v[64:65], v[64:65], v[132:133] op_sel_hi:[1,1,0]
	s_nop 0
	v_mov_b32_e32 v133, v134
	v_pk_add_f32 v[128:129], v[128:129], v[132:133]
	s_waitcnt vmcnt(1)
	v_mul_f32_e32 v132, v72, v72
	v_pk_add_f32 v[124:125], v[124:125], v[128:129]
	v_mul_f32_e32 v128, v70, v70
	v_add_f32_e32 v123, v124, v125
	v_mul_f32_e32 v129, v71, v71
	v_pk_add_f32 v[124:125], v[126:127], v[126:127] op_sel:[0,1] op_sel_hi:[1,0]
	v_pk_add_f32 v[126:127], v[130:131], v[130:131] op_sel:[0,1] op_sel_hi:[1,0]
	v_mov_b32_e32 v125, v128
	v_mov_b32_e32 v127, v129
	v_pk_add_f32 v[124:125], v[124:125], v[126:127]
	v_mul_f32_e32 v126, v31, v31
	v_mul_f32_e32 v128, v33, v33
	v_mul_f32_e32 v133, v73, v73
	v_pk_fma_f32 v[126:127], v[30:31], v[30:31], v[126:127] op_sel_hi:[1,1,0]
	v_pk_fma_f32 v[128:129], v[32:33], v[32:33], v[128:129] op_sel_hi:[1,1,0]
	v_mov_b32_e32 v127, v132
	v_mov_b32_e32 v129, v133
	v_pk_add_f32 v[126:127], v[126:127], v[128:129]
	s_nop 0
	v_pk_add_f32 v[124:125], v[124:125], v[126:127]
	s_nop 0
	v_add_f32_e32 v125, v124, v125
	ds_bpermute_b32 v124, v122, v123
	s_waitcnt lgkmcnt(0)
	v_add_f32_e32 v123, v123, v124
	ds_bpermute_b32 v124, v121, v123
	s_waitcnt lgkmcnt(0)
	v_add_f32_e32 v123, v123, v124
	ds_bpermute_b32 v124, v120, v123
	s_waitcnt lgkmcnt(0)
	v_add_f32_e32 v123, v123, v124
	ds_bpermute_b32 v124, v119, v123
	s_waitcnt lgkmcnt(0)
	v_add_f32_e32 v123, v123, v124
	ds_bpermute_b32 v124, v118, v123
	s_waitcnt lgkmcnt(0)
	v_add_f32_e32 v123, v123, v124
	ds_bpermute_b32 v124, v0, v123
	s_waitcnt lgkmcnt(0)
	v_add_f32_e32 v123, v123, v124
	v_fmamk_f32 v123, v123, 0x3a000000, v200
	v_cmp_gt_f32_e32 vcc, s19, v123
	v_mul_f32_e32 v124, 0x4f800000, v123
	s_nop 0
	v_cndmask_b32_e32 v123, v123, v124, vcc
	v_sqrt_f32_e32 v124, v123
	s_nop 0
	v_add_u32_e32 v126, -1, v124
	v_fma_f32 v127, -v126, v124, v123
	v_cmp_ge_f32_e64 s[6:7], 0, v127
	v_add_u32_e32 v127, 1, v124
	s_nop 0
	v_cndmask_b32_e64 v126, v124, v126, s[6:7]
	v_fma_f32 v124, -v127, v124, v123
	v_cmp_lt_f32_e64 s[6:7], 0, v124
	s_nop 1
	v_cndmask_b32_e64 v124, v126, v127, s[6:7]
	v_mul_f32_e32 v126, 0x37800000, v124
	v_cndmask_b32_e32 v124, v124, v126, vcc
	v_cmp_class_f32_e32 vcc, v123, v201
	s_nop 1
	v_cndmask_b32_e32 v123, v124, v123, vcc
	v_div_scale_f32 v124, s[4:5], v123, v123, 1.0
	v_rcp_f32_e32 v126, v124
	s_nop 0
	v_fma_f32 v127, -v124, v126, 1.0
	v_fmac_f32_e32 v126, v127, v126
	v_div_scale_f32 v127, vcc, 1.0, v123, 1.0
	v_mul_f32_e32 v128, v127, v126
	v_fma_f32 v129, -v124, v128, v127
	v_fmac_f32_e32 v128, v129, v126
	v_fma_f32 v124, -v124, v128, v127
	v_div_fmas_f32 v124, v124, v126, v128
	v_div_fixup_f32 v124, v124, v123, 1.0
	ds_bpermute_b32 v123, v122, v125
	s_waitcnt lgkmcnt(0)
	v_add_f32_e32 v123, v125, v123
	ds_bpermute_b32 v125, v121, v123
	s_waitcnt lgkmcnt(0)
	v_add_f32_e32 v123, v123, v125
	ds_bpermute_b32 v125, v120, v123
	s_waitcnt lgkmcnt(0)
	v_add_f32_e32 v123, v123, v125
	ds_bpermute_b32 v125, v119, v123
	s_waitcnt lgkmcnt(0)
	v_add_f32_e32 v123, v123, v125
	ds_bpermute_b32 v125, v118, v123
	s_waitcnt lgkmcnt(0)
	v_add_f32_e32 v123, v123, v125
	ds_bpermute_b32 v125, v0, v123
	s_waitcnt lgkmcnt(0)
	v_add_f32_e32 v123, v123, v125
	v_fmamk_f32 v123, v123, 0x3a000000, v200
	v_cmp_gt_f32_e32 vcc, s19, v123
	v_mul_f32_e32 v125, 0x4f800000, v123
	s_nop 0
	v_cndmask_b32_e32 v123, v123, v125, vcc
	v_sqrt_f32_e32 v125, v123
	s_nop 0
	v_add_u32_e32 v126, -1, v125
	v_fma_f32 v127, -v126, v125, v123
	v_cmp_ge_f32_e64 s[6:7], 0, v127
	v_add_u32_e32 v127, 1, v125
	s_nop 0
	v_cndmask_b32_e64 v126, v125, v126, s[6:7]
	v_fma_f32 v125, -v127, v125, v123
	v_cmp_lt_f32_e64 s[6:7], 0, v125
	s_nop 1
	v_cndmask_b32_e64 v125, v126, v127, s[6:7]
	v_mul_f32_e32 v126, 0x37800000, v125
	v_cndmask_b32_e32 v125, v125, v126, vcc
	v_cmp_class_f32_e32 vcc, v123, v201
	v_readlane_b32 s6, v255, 20
	v_readlane_b32 s7, v255, 21
	v_cndmask_b32_e32 v123, v125, v123, vcc
	v_div_scale_f32 v125, s[4:5], v123, v123, 1.0
	v_rcp_f32_e32 v126, v125
	s_lshl_b64 s[4:5], s[14:15], 12
	s_add_i32 s14, s1, s16
	v_fma_f32 v127, -v125, v126, 1.0
	v_fmac_f32_e32 v126, v127, v126
	v_div_scale_f32 v127, vcc, 1.0, v123, 1.0
	v_mul_f32_e32 v128, v127, v126
	v_fma_f32 v129, -v125, v128, v127
	v_fmac_f32_e32 v128, v129, v126
	v_fma_f32 v125, -v125, v128, v127
	v_div_fmas_f32 v125, v125, v126, v128
	v_div_fixup_f32 v126, v125, v123, 1.0
	v_pk_mul_f32 v[82:83], v[82:83], v[124:125] op_sel_hi:[1,0]
	v_pk_mul_f32 v[84:85], v[84:85], v[124:125] op_sel_hi:[1,0]
	v_pk_mul_f32 v[50:51], v[50:51], v[126:127] op_sel_hi:[1,0]
	v_pk_mul_f32 v[52:53], v[52:53], v[126:127] op_sel_hi:[1,0]
	v_pk_mul_f32 v[82:83], v[54:55], v[82:83]
	v_pk_mul_f32 v[84:85], v[56:57], v[84:85]
	v_pk_mul_f32 v[50:51], v[54:55], v[50:51]
	v_pk_mul_f32 v[52:53], v[56:57], v[52:53]
	v_lshl_add_u64 v[128:129], v[102:103], 0, s[4:5]
	v_cvt_pk_bf16_f32 v82, v82, v83
	v_cvt_pk_bf16_f32 v83, v84, v85
	v_cvt_pk_bf16_f32 v50, v50, v51
	v_cvt_pk_bf16_f32 v51, v52, v53
	global_store_dwordx2 v[116:117], v[82:83], off sc1
	global_store_dwordx2 v[128:129], v[50:51], off sc1
	v_pk_mul_f32 v[50:51], v[66:67], v[124:125] op_sel_hi:[1,0]
	v_pk_mul_f32 v[52:53], v[68:69], v[124:125] op_sel_hi:[1,0]
	v_pk_mul_f32 v[38:39], v[38:39], v[126:127] op_sel_hi:[1,0]
	v_pk_mul_f32 v[40:41], v[40:41], v[126:127] op_sel_hi:[1,0]
	v_pk_mul_f32 v[50:51], v[42:43], v[50:51]
	v_pk_mul_f32 v[52:53], v[44:45], v[52:53]
	v_pk_mul_f32 v[38:39], v[42:43], v[38:39]
	v_pk_mul_f32 v[40:41], v[44:45], v[40:41]
	v_cvt_pk_bf16_f32 v50, v50, v51
	v_cvt_pk_bf16_f32 v51, v52, v53
	v_cvt_pk_bf16_f32 v38, v38, v39
	v_cvt_pk_bf16_f32 v39, v40, v41
	global_store_dwordx2 v[116:117], v[50:51], off offset:512 sc1
	global_store_dwordx2 v[128:129], v[38:39], off offset:512 sc1
	v_pk_mul_f32 v[38:39], v[58:59], v[124:125] op_sel_hi:[1,0]
	v_pk_mul_f32 v[40:41], v[60:61], v[124:125] op_sel_hi:[1,0]
	v_pk_mul_f32 v[14:15], v[14:15], v[126:127] op_sel_hi:[1,0]
	v_pk_mul_f32 v[16:17], v[16:17], v[126:127] op_sel_hi:[1,0]
	v_pk_mul_f32 v[10:11], v[10:11], v[124:125] op_sel_hi:[1,0]
	v_pk_mul_f32 v[12:13], v[12:13], v[124:125] op_sel_hi:[1,0]
	v_pk_mul_f32 v[2:3], v[2:3], v[126:127] op_sel_hi:[1,0]
	v_pk_mul_f32 v[4:5], v[4:5], v[126:127] op_sel_hi:[1,0]
	v_pk_mul_f32 v[38:39], v[18:19], v[38:39]
	v_pk_mul_f32 v[40:41], v[20:21], v[40:41]
	v_pk_mul_f32 v[14:15], v[18:19], v[14:15]
	v_pk_mul_f32 v[16:17], v[20:21], v[16:17]
	v_pk_mul_f32 v[10:11], v[6:7], v[10:11]
	v_pk_mul_f32 v[12:13], v[8:9], v[12:13]
	v_pk_mul_f32 v[2:3], v[6:7], v[2:3]
	v_pk_mul_f32 v[4:5], v[8:9], v[4:5]
	v_cvt_pk_bf16_f32 v38, v38, v39
	v_cvt_pk_bf16_f32 v39, v40, v41
	v_cvt_pk_bf16_f32 v14, v14, v15
	v_cvt_pk_bf16_f32 v15, v16, v17
	v_cvt_pk_bf16_f32 v10, v10, v11
	v_cvt_pk_bf16_f32 v11, v12, v13
	v_cvt_pk_bf16_f32 v2, v2, v3
	v_cvt_pk_bf16_f32 v3, v4, v5
	global_store_dwordx2 v[116:117], v[38:39], off offset:1024 sc1
	global_store_dwordx2 v[128:129], v[14:15], off offset:1024 sc1
	global_store_dwordx2 v[116:117], v[10:11], off offset:1536 sc1
	global_store_dwordx2 v[128:129], v[2:3], off offset:1536 sc1
	v_pk_mul_f32 v[2:3], v[46:47], v[124:125] op_sel_hi:[1,0]
	v_pk_mul_f32 v[4:5], v[48:49], v[124:125] op_sel_hi:[1,0]
	v_pk_mul_f32 v[2:3], v[26:27], v[2:3]
	v_pk_mul_f32 v[4:5], v[28:29], v[4:5]
	v_cvt_pk_bf16_f32 v2, v2, v3
	v_cvt_pk_bf16_f32 v3, v4, v5
	global_store_dwordx2 v[116:117], v[2:3], off offset:2048 sc1
	v_pk_mul_f32 v[2:3], v[22:23], v[126:127] op_sel_hi:[1,0]
	v_pk_mul_f32 v[4:5], v[24:25], v[126:127] op_sel_hi:[1,0]
	v_pk_mul_f32 v[2:3], v[26:27], v[2:3]
	v_pk_mul_f32 v[4:5], v[28:29], v[4:5]
	v_cvt_pk_bf16_f32 v2, v2, v3
	v_cvt_pk_bf16_f32 v3, v4, v5
	global_store_dwordx2 v[128:129], v[2:3], off offset:2048 sc1
	v_pk_mul_f32 v[2:3], v[90:91], v[124:125] op_sel_hi:[1,0]
	v_pk_mul_f32 v[4:5], v[92:93], v[124:125] op_sel_hi:[1,0]
	v_pk_mul_f32 v[2:3], v[78:79], v[2:3]
	v_pk_mul_f32 v[4:5], v[80:81], v[4:5]
	v_cvt_pk_bf16_f32 v2, v2, v3
	v_cvt_pk_bf16_f32 v3, v4, v5
	global_store_dwordx2 v[116:117], v[2:3], off offset:2560 sc1
	v_pk_mul_f32 v[2:3], v[74:75], v[126:127] op_sel_hi:[1,0]
	v_pk_mul_f32 v[4:5], v[76:77], v[126:127] op_sel_hi:[1,0]
	v_pk_mul_f32 v[2:3], v[78:79], v[2:3]
	v_pk_mul_f32 v[4:5], v[80:81], v[4:5]
	v_cvt_pk_bf16_f32 v2, v2, v3
	v_cvt_pk_bf16_f32 v3, v4, v5
	global_store_dwordx2 v[128:129], v[2:3], off offset:2560 sc1
	v_pk_mul_f32 v[2:3], v[62:63], v[124:125] op_sel_hi:[1,0]
	v_pk_mul_f32 v[4:5], v[64:65], v[124:125] op_sel_hi:[1,0]
	v_pk_mul_f32 v[2:3], v[34:35], v[2:3]
	v_pk_mul_f32 v[4:5], v[36:37], v[4:5]
	v_cvt_pk_bf16_f32 v2, v2, v3
	v_cvt_pk_bf16_f32 v3, v4, v5
	global_store_dwordx2 v[116:117], v[2:3], off offset:3072 sc1
	v_pk_mul_f32 v[2:3], v[30:31], v[126:127] op_sel_hi:[1,0]
	v_pk_mul_f32 v[4:5], v[32:33], v[126:127] op_sel_hi:[1,0]
	v_pk_mul_f32 v[2:3], v[34:35], v[2:3]
	v_pk_mul_f32 v[4:5], v[36:37], v[4:5]
	v_cvt_pk_bf16_f32 v2, v2, v3
	v_cvt_pk_bf16_f32 v3, v4, v5
	global_store_dwordx2 v[128:129], v[2:3], off offset:3072 sc1
	v_pk_mul_f32 v[2:3], v[86:87], v[124:125] op_sel_hi:[1,0]
	v_pk_mul_f32 v[4:5], v[88:89], v[124:125] op_sel_hi:[1,0]
	s_waitcnt vmcnt(14)
	v_pk_mul_f32 v[2:3], v[94:95], v[2:3]
	v_pk_mul_f32 v[4:5], v[96:97], v[4:5]
	v_cvt_pk_bf16_f32 v2, v2, v3
	v_cvt_pk_bf16_f32 v3, v4, v5
	global_store_dwordx2 v[116:117], v[2:3], off offset:3584 sc1
	v_pk_mul_f32 v[2:3], v[70:71], v[126:127] op_sel_hi:[1,0]
	v_pk_mul_f32 v[4:5], v[72:73], v[126:127] op_sel_hi:[1,0]
	v_pk_mul_f32 v[2:3], v[94:95], v[2:3]
	v_pk_mul_f32 v[4:5], v[96:97], v[4:5]
	s_add_i32 s4, s17, s0
	v_cvt_pk_bf16_f32 v2, v2, v3
	v_cvt_pk_bf16_f32 v3, v4, v5
	v_lshl_add_u64 v[116:117], v[116:117], 0, s[6:7]
	s_cmpk_lt_i32 s4, 0x4000
	global_store_dwordx2 v[128:129], v[2:3], off offset:3584 sc1
	s_cbranch_scc1 .LBB0_644
	v_readlane_b32 s1, v254, 0
	s_mov_b32 s58, 0xf800000
	s_add_i32 s14, s1, s0
.LBB0_646:
	s_cmpk_gt_i32 s14, 0x3fff
	s_cbranch_scc1 .LBB0_648
	s_ashr_i32 s15, s14, 31
	s_lshl_b64 s[0:1], s[14:15], 13
	s_add_u32 s4, s12, s0
	s_addc_u32 s5, s13, s1
	v_lshlrev_b64 v[34:35], 4, v[98:99]
	v_lshl_add_u64 v[6:7], s[4:5], 0, v[34:35]
	s_load_dwordx2 s[6:7], s[8:9], 0x18
	global_load_dwordx4 v[10:13], v[6:7], off
	global_load_dwordx4 v[2:5], v[6:7], off offset:1024
	v_add_co_u32_e32 v26, vcc, s57, v6
	s_mov_b64 s[4:5], 0x2000
	s_nop 0
	v_addc_co_u32_e32 v27, vcc, 0, v7, vcc
	s_waitcnt lgkmcnt(0)
	v_lshl_add_u64 v[34:35], s[6:7], 0, v[34:35]
	s_lshl_b64 s[0:1], s[14:15], 12
	s_add_u32 s0, s10, s0
	s_addc_u32 s1, s11, s1
	s_waitcnt vmcnt(1)
	v_mov_b32_e32 v14, v11
	s_waitcnt vmcnt(0)
	v_mov_b32_e32 v15, v3
	v_mov_b32_e32 v8, v10
	v_mov_b32_e32 v9, v2
	v_pk_mul_f32 v[14:15], v[14:15], v[14:15]
	v_mov_b32_e32 v16, v13
	v_mov_b32_e32 v17, v5
	v_pk_fma_f32 v[8:9], v[8:9], v[8:9], v[14:15]
	v_mov_b32_e32 v14, v12
	v_mov_b32_e32 v15, v4
	v_pk_mul_f32 v[16:17], v[16:17], v[16:17]
	s_nop 0
	v_pk_fma_f32 v[14:15], v[14:15], v[14:15], v[16:17]
	s_nop 0
	v_pk_add_f32 v[22:23], v[8:9], v[14:15]
	global_load_dwordx4 v[14:17], v[6:7], off offset:2048
	v_pk_add_f32 v[22:23], v[22:23], v[22:23] op_sel:[0,1] op_sel_hi:[1,0]
	s_waitcnt vmcnt(0)
	v_pk_mul_f32 v[8:9], v[16:17], v[16:17]
	v_pk_mul_f32 v[18:19], v[14:15], v[14:15]
	s_nop 0
	v_pk_mov_b32 v[20:21], v[18:19], v[8:9] op_sel:[1,0]
	v_mov_b32_e32 v19, v9
	v_pk_add_f32 v[24:25], v[20:21], v[18:19]
	global_load_dwordx4 v[18:21], v[6:7], off offset:3072
	v_pk_add_f32 v[24:25], v[24:25], v[24:25] op_sel:[0,1] op_sel_hi:[1,0]
	global_load_dwordx4 v[6:9], v[26:27], off
	s_waitcnt vmcnt(0)
	v_mul_f32_e32 v28, v6, v6
	v_mul_f32_e32 v29, v7, v7
	v_mov_b32_e32 v23, v28
	v_mov_b32_e32 v25, v29
	v_pk_add_f32 v[22:23], v[22:23], v[24:25]
	v_mul_f32_e32 v24, v19, v19
	v_mul_f32_e32 v28, v21, v21
	v_mul_f32_e32 v30, v8, v8
	v_mul_f32_e32 v31, v9, v9
	v_pk_fma_f32 v[24:25], v[18:19], v[18:19], v[24:25] op_sel_hi:[1,1,0]
	v_pk_fma_f32 v[28:29], v[20:21], v[20:21], v[28:29] op_sel_hi:[1,1,0]
	v_mov_b32_e32 v25, v30
	v_mov_b32_e32 v29, v31
	global_load_dwordx4 v[30:33], v[26:27], off offset:1024
	v_pk_add_f32 v[24:25], v[24:25], v[28:29]
	s_nop 0
	v_pk_add_f32 v[36:37], v[22:23], v[24:25]
	s_waitcnt vmcnt(0)
	v_pk_mul_f32 v[22:23], v[32:33], v[32:33]
	v_pk_mul_f32 v[24:25], v[30:31], v[30:31]
	v_pk_add_f32 v[36:37], v[36:37], v[36:37] op_sel:[0,1] op_sel_hi:[1,0]
	v_pk_mov_b32 v[28:29], v[24:25], v[22:23] op_sel:[1,0]
	v_mov_b32_e32 v25, v23
	v_pk_add_f32 v[38:39], v[28:29], v[24:25]
	global_load_dwordx4 v[22:25], v[26:27], off offset:2048
	s_nop 0
	global_load_dwordx4 v[26:29], v[26:27], off offset:3072
	v_pk_add_f32 v[38:39], v[38:39], v[38:39] op_sel:[0,1] op_sel_hi:[1,0]
	s_waitcnt vmcnt(0)
	v_mul_f32_e32 v40, v26, v26
	v_mul_f32_e32 v41, v27, v27
	v_mov_b32_e32 v37, v40
	v_mov_b32_e32 v39, v41
	v_pk_add_f32 v[36:37], v[36:37], v[38:39]
	v_mul_f32_e32 v38, v23, v23
	v_mul_f32_e32 v40, v25, v25
	v_mul_f32_e32 v42, v28, v28
	v_mul_f32_e32 v43, v29, v29
	v_pk_fma_f32 v[38:39], v[22:23], v[22:23], v[38:39] op_sel_hi:[1,1,0]
	v_pk_fma_f32 v[40:41], v[24:25], v[24:25], v[40:41] op_sel_hi:[1,1,0]
	v_mov_b32_e32 v39, v42
	v_mov_b32_e32 v41, v43
	v_pk_add_f32 v[38:39], v[38:39], v[40:41]
	v_lshl_add_u64 v[40:41], v[34:35], 0, s[4:5]
	v_pk_add_f32 v[36:37], v[36:37], v[38:39]
	s_nop 0
	v_add_f32_e32 v36, v36, v37
	ds_bpermute_b32 v37, v122, v36
	s_waitcnt lgkmcnt(0)
	v_add_f32_e32 v36, v36, v37
	ds_bpermute_b32 v37, v121, v36
	s_waitcnt lgkmcnt(0)
	v_add_f32_e32 v36, v36, v37
	ds_bpermute_b32 v37, v120, v36
	s_waitcnt lgkmcnt(0)
	v_add_f32_e32 v36, v36, v37
	ds_bpermute_b32 v37, v119, v36
	s_waitcnt lgkmcnt(0)
	v_add_f32_e32 v36, v36, v37
	ds_bpermute_b32 v37, v118, v36
	s_waitcnt lgkmcnt(0)
	v_add_f32_e32 v36, v36, v37
	ds_bpermute_b32 v0, v0, v36
	s_waitcnt lgkmcnt(0)
	v_add_f32_e32 v0, v36, v0
	v_fmamk_f32 v0, v0, 0x3a000000, v200
	v_cmp_gt_f32_e32 vcc, s58, v0
	v_mul_f32_e32 v36, 0x4f800000, v0
	s_nop 0
	v_cndmask_b32_e32 v0, v0, v36, vcc
	v_sqrt_f32_e32 v36, v0
	s_nop 0
	v_add_u32_e32 v37, -1, v36
	v_fma_f32 v38, -v37, v36, v0
	v_cmp_ge_f32_e64 s[6:7], 0, v38
	v_add_u32_e32 v38, 1, v36
	s_nop 0
	v_cndmask_b32_e64 v37, v36, v37, s[6:7]
	v_fma_f32 v36, -v38, v36, v0
	v_cmp_lt_f32_e64 s[6:7], 0, v36
	s_nop 1
	v_cndmask_b32_e64 v36, v37, v38, s[6:7]
	v_mul_f32_e32 v37, 0x37800000, v36
	v_cndmask_b32_e32 v36, v36, v37, vcc
	v_cmp_class_f32_e32 vcc, v0, v201
	s_nop 1
	v_cndmask_b32_e32 v0, v36, v0, vcc
	v_div_scale_f32 v36, s[4:5], v0, v0, 1.0
	v_rcp_f32_e32 v37, v36
	s_nop 0
	v_fma_f32 v38, -v36, v37, 1.0
	v_fmac_f32_e32 v37, v38, v37
	v_div_scale_f32 v38, vcc, 1.0, v0, 1.0
	v_mul_f32_e32 v39, v38, v37
	v_fma_f32 v42, -v36, v39, v38
	v_fmac_f32_e32 v39, v42, v37
	v_fma_f32 v36, -v36, v39, v38
	v_div_fmas_f32 v36, v36, v37, v39
	v_lshl_add_u64 v[38:39], v[98:99], 3, s[0:1]
	s_movk_i32 s0, 0x3000
	v_add_co_u32_e32 v42, vcc, s0, v34
	v_div_fixup_f32 v0, v36, v0, 1.0
	s_nop 0
	v_addc_co_u32_e32 v43, vcc, 0, v35, vcc
	global_load_dwordx4 v[34:37], v[42:43], off offset:-4096
	v_pk_mul_f32 v[10:11], v[10:11], v[0:1] op_sel_hi:[1,0]
	v_pk_mul_f32 v[12:13], v[12:13], v[0:1] op_sel_hi:[1,0]
	v_pk_mul_f32 v[2:3], v[2:3], v[0:1] op_sel_hi:[1,0]
	v_pk_mul_f32 v[4:5], v[4:5], v[0:1] op_sel_hi:[1,0]
	v_pk_mul_f32 v[6:7], v[6:7], v[0:1] op_sel_hi:[1,0]
	s_waitcnt vmcnt(0)
	v_pk_mul_f32 v[10:11], v[34:35], v[10:11]
	v_pk_mul_f32 v[12:13], v[36:37], v[12:13]
	v_cvt_pk_bf16_f32 v10, v10, v11
	v_cvt_pk_bf16_f32 v11, v12, v13
	global_store_dwordx2 v[38:39], v[10:11], off sc1
	global_load_dwordx4 v[10:13], v[40:41], off offset:1024
	s_waitcnt vmcnt(0)
	v_pk_mul_f32 v[2:3], v[10:11], v[2:3]
	v_pk_mul_f32 v[4:5], v[12:13], v[4:5]
	v_cvt_pk_bf16_f32 v2, v2, v3
	v_cvt_pk_bf16_f32 v3, v4, v5
	global_store_dwordx2 v[38:39], v[2:3], off offset:512 sc1
	global_load_dwordx4 v[2:5], v[40:41], off offset:2048
	v_pk_mul_f32 v[10:11], v[14:15], v[0:1] op_sel_hi:[1,0]
	s_waitcnt vmcnt(0)
	v_pk_mul_f32 v[2:3], v[2:3], v[10:11]
	v_pk_mul_f32 v[10:11], v[16:17], v[0:1] op_sel_hi:[1,0]
	v_cvt_pk_bf16_f32 v2, v2, v3
	v_pk_mul_f32 v[4:5], v[4:5], v[10:11]
	v_pk_mul_f32 v[10:11], v[18:19], v[0:1] op_sel_hi:[1,0]
	v_cvt_pk_bf16_f32 v3, v4, v5
	global_store_dwordx2 v[38:39], v[2:3], off offset:1024 sc1
	global_load_dwordx4 v[2:5], v[40:41], off offset:3072
	s_waitcnt vmcnt(0)
	v_pk_mul_f32 v[2:3], v[2:3], v[10:11]
	v_pk_mul_f32 v[10:11], v[20:21], v[0:1] op_sel_hi:[1,0]
	v_cvt_pk_bf16_f32 v2, v2, v3
	v_pk_mul_f32 v[4:5], v[4:5], v[10:11]
	s_nop 0
	v_cvt_pk_bf16_f32 v3, v4, v5
	global_store_dwordx2 v[38:39], v[2:3], off offset:1536 sc1
	global_load_dwordx4 v[2:5], v[42:43], off
	s_waitcnt vmcnt(0)
	v_pk_mul_f32 v[2:3], v[6:7], v[2:3]
	v_pk_mul_f32 v[6:7], v[8:9], v[0:1] op_sel_hi:[1,0]
	v_cvt_pk_bf16_f32 v2, v2, v3
	v_pk_mul_f32 v[4:5], v[6:7], v[4:5]
	v_pk_mul_f32 v[6:7], v[30:31], v[0:1] op_sel_hi:[1,0]
	v_cvt_pk_bf16_f32 v3, v4, v5
	global_store_dwordx2 v[38:39], v[2:3], off offset:2048 sc1
	global_load_dwordx4 v[2:5], v[42:43], off offset:1024
	s_waitcnt vmcnt(0)
	v_pk_mul_f32 v[2:3], v[6:7], v[2:3]
	v_pk_mul_f32 v[6:7], v[32:33], v[0:1] op_sel_hi:[1,0]
	v_cvt_pk_bf16_f32 v2, v2, v3
	v_pk_mul_f32 v[4:5], v[6:7], v[4:5]
	v_pk_mul_f32 v[6:7], v[22:23], v[0:1] op_sel_hi:[1,0]
	v_cvt_pk_bf16_f32 v3, v4, v5
	global_store_dwordx2 v[38:39], v[2:3], off offset:2560 sc1
	global_load_dwordx4 v[2:5], v[42:43], off offset:2048
	s_waitcnt vmcnt(0)
	v_pk_mul_f32 v[2:3], v[6:7], v[2:3]
	v_pk_mul_f32 v[6:7], v[24:25], v[0:1] op_sel_hi:[1,0]
	v_cvt_pk_bf16_f32 v2, v2, v3
	v_pk_mul_f32 v[4:5], v[6:7], v[4:5]
	v_pk_mul_f32 v[6:7], v[26:27], v[0:1] op_sel_hi:[1,0]
	v_cvt_pk_bf16_f32 v3, v4, v5
	global_store_dwordx2 v[38:39], v[2:3], off offset:3072 sc1
	global_load_dwordx4 v[2:5], v[42:43], off offset:3072
	s_waitcnt vmcnt(0)
	v_pk_mul_f32 v[2:3], v[6:7], v[2:3]
	v_pk_mul_f32 v[6:7], v[28:29], v[0:1] op_sel_hi:[1,0]
	v_cvt_pk_bf16_f32 v2, v2, v3
	v_pk_mul_f32 v[4:5], v[6:7], v[4:5]
	s_nop 0
	v_cvt_pk_bf16_f32 v3, v4, v5
	global_store_dwordx2 v[38:39], v[2:3], off offset:3584 sc1

.LBB0_702:
	global_load_dwordx4 v[12:15], v[78:79], off offset:-4096
	global_load_dwordx4 v[16:19], v[78:79], off offset:-3072
	global_load_dwordx4 v[20:23], v[78:79], off offset:-2048
	global_load_dwordx4 v[24:27], v[78:79], off
	global_load_dwordx4 v[28:31], v[78:79], off offset:1024
	global_load_dwordx4 v[36:39], v[78:79], off offset:-1024
	global_load_dwordx4 v[32:35], v[78:79], off offset:3072
	global_load_dwordx4 v[40:43], v[78:79], off offset:2048
	s_ashr_i32 s13, s12, 31
	s_lshl_b64 s[2:3], s[12:13], 13
	v_lshl_add_u64 v[82:83], v[76:77], 0, s[2:3]
	global_load_dwordx4 v[8:11], v[64:65], off
	global_load_dwordx4 v[4:7], v[64:65], off offset:1024
	global_load_dwordx4 v[0:3], v[64:65], off offset:2048
	global_load_dwordx4 v[44:47], v[64:65], off offset:3072
	global_load_dwordx4 v[48:51], v[68:69], off
	global_load_dwordx4 v[52:55], v[70:71], off
	global_load_dwordx4 v[56:59], v[72:73], off
	global_load_dwordx4 v[60:63], v[74:75], off
	global_load_dwordx4 v[94:97], v[82:83], off
	global_load_dwordx4 v[98:101], v[82:83], off offset:1024
	global_load_dwordx4 v[102:105], v[82:83], off offset:2048
	global_load_dwordx4 v[106:109], v[82:83], off offset:3072
	v_add_co_u32_e32 v80, vcc, s0, v82
	s_add_i32 s8, s8, s14
	s_nop 0
	v_addc_co_u32_e32 v81, vcc, 0, v83, vcc
	global_load_dwordx4 v[110:113], v[80:81], off offset:1024
	global_load_dwordx4 v[114:117], v[80:81], off
	global_load_dwordx4 v[118:121], v[80:81], off offset:3072
	global_load_dwordx4 v[122:125], v[80:81], off offset:2048
	s_add_i32 s6, s6, s14
	s_add_i32 s12, s8, s10
	s_add_i32 s4, s7, s6
	s_cmpk_lt_i32 s4, 0x4000
	s_waitcnt vmcnt(23)
	v_mov_b32_e32 v128, v13
	s_waitcnt vmcnt(22)
	v_mov_b32_e32 v129, v17
	v_mov_b32_e32 v132, v15
	v_mov_b32_e32 v133, v19
	v_mov_b32_e32 v126, v12
	v_mov_b32_e32 v127, v16
	v_mov_b32_e32 v130, v14
	v_mov_b32_e32 v131, v18
	s_waitcnt vmcnt(21)
	v_pk_mul_f32 v[134:135], v[22:23], v[22:23]
	v_pk_mul_f32 v[136:137], v[20:21], v[20:21]
	s_waitcnt vmcnt(20)
	v_mul_f32_e32 v149, v25, v25
	s_waitcnt vmcnt(19)
	v_pk_mul_f32 v[138:139], v[30:31], v[30:31]
	v_pk_mul_f32 v[140:141], v[28:29], v[28:29]
	s_waitcnt vmcnt(18)
	v_mul_f32_e32 v142, v37, v37
	v_mul_f32_e32 v144, v39, v39
	s_waitcnt vmcnt(16)
	v_mul_f32_e32 v146, v41, v41
	v_mul_f32_e32 v148, v43, v43
	v_pk_mul_f32 v[128:129], v[128:129], v[128:129]
	v_pk_mul_f32 v[132:133], v[132:133], v[132:133]
	v_mul_f32_e32 v152, v26, v26
	v_mul_f32_e32 v153, v27, v27
	v_mul_f32_e32 v154, v34, v34
	v_mul_f32_e32 v155, v35, v35
	v_pk_mov_b32 v[150:151], v[136:137], v[134:135] op_sel:[1,0]
	v_mov_b32_e32 v137, v135
	v_pk_mov_b32 v[134:135], v[140:141], v[138:139] op_sel:[1,0]
	v_mov_b32_e32 v141, v139
	v_pk_fma_f32 v[138:139], v[36:37], v[36:37], v[142:143] op_sel_hi:[1,1,0]
	v_pk_fma_f32 v[142:143], v[38:39], v[38:39], v[144:145] op_sel_hi:[1,1,0]
	v_pk_fma_f32 v[144:145], v[40:41], v[40:41], v[146:147] op_sel_hi:[1,1,0]
	v_pk_fma_f32 v[146:147], v[42:43], v[42:43], v[148:149] op_sel_hi:[1,1,0]
	v_pk_fma_f32 v[126:127], v[126:127], v[126:127], v[128:129]
	v_pk_fma_f32 v[128:129], v[130:131], v[130:131], v[132:133]
	v_pk_add_f32 v[130:131], v[150:151], v[136:137]
	v_mov_b32_e32 v139, v152
	v_mov_b32_e32 v143, v153
	v_mov_b32_e32 v145, v154
	v_mov_b32_e32 v147, v155
	v_pk_add_f32 v[126:127], v[126:127], v[128:129]
	v_mul_f32_e32 v93, v24, v24
	v_pk_add_f32 v[132:133], v[134:135], v[140:141]
	s_waitcnt vmcnt(7)
	v_mov_b32_e32 v134, v95
	s_waitcnt vmcnt(6)
	v_mov_b32_e32 v135, v99
	s_waitcnt vmcnt(5)
	v_pk_mul_f32 v[136:137], v[104:105], v[104:105]
	v_pk_add_f32 v[138:139], v[138:139], v[142:143]
	v_pk_mul_f32 v[140:141], v[102:103], v[102:103]
	v_pk_add_f32 v[142:143], v[144:145], v[146:147]
	v_mov_b32_e32 v146, v97
	v_mov_b32_e32 v147, v101
	v_pk_add_f32 v[130:131], v[130:131], v[130:131] op_sel:[0,1] op_sel_hi:[1,0]
	v_pk_add_f32 v[126:127], v[126:127], v[126:127] op_sel:[0,1] op_sel_hi:[1,0]
	v_mov_b32_e32 v128, v94
	v_mov_b32_e32 v129, v98
	v_mov_b32_e32 v144, v96
	v_mov_b32_e32 v145, v100
	v_pk_mov_b32 v[152:153], v[140:141], v[136:137] op_sel:[1,0]
	v_mov_b32_e32 v141, v137
	v_pk_mul_f32 v[134:135], v[134:135], v[134:135]
	v_pk_mul_f32 v[136:137], v[146:147], v[146:147]
	v_mov_b32_e32 v131, v149
	v_mov_b32_e32 v127, v93
	v_pk_fma_f32 v[128:129], v[128:129], v[128:129], v[134:135]
	v_pk_fma_f32 v[134:135], v[144:145], v[144:145], v[136:137]
	v_pk_add_f32 v[126:127], v[126:127], v[130:131]
	v_mul_f32_e32 v159, v33, v33
	s_waitcnt vmcnt(4)
	v_mul_f32_e32 v148, v107, v107
	v_mul_f32_e32 v150, v109, v109
	v_pk_add_f32 v[132:133], v[132:133], v[132:133] op_sel:[0,1] op_sel_hi:[1,0]
	v_pk_add_f32 v[136:137], v[152:153], v[140:141]
	v_pk_add_f32 v[128:129], v[128:129], v[134:135]
	v_pk_add_f32 v[126:127], v[126:127], v[138:139]
	v_mul_f32_e32 v157, v32, v32
	s_waitcnt vmcnt(2)
	v_mul_f32_e32 v160, v116, v116
	v_mul_f32_e32 v161, v117, v117
	v_pk_fma_f32 v[148:149], v[106:107], v[106:107], v[148:149] op_sel_hi:[1,1,0]
	v_pk_fma_f32 v[150:151], v[108:109], v[108:109], v[150:151] op_sel_hi:[1,1,0]
	v_mov_b32_e32 v133, v159
	v_mul_f32_e32 v159, v115, v115
	v_mul_f32_e32 v164, v114, v114
	v_pk_add_f32 v[136:137], v[136:137], v[136:137] op_sel:[0,1] op_sel_hi:[1,0]
	v_pk_add_f32 v[128:129], v[128:129], v[128:129] op_sel:[0,1] op_sel_hi:[1,0]
	v_pk_add_f32 v[126:127], v[126:127], v[126:127] op_sel:[0,1] op_sel_hi:[1,0]
	v_pk_mul_f32 v[146:147], v[112:113], v[112:113]
	v_pk_mul_f32 v[154:155], v[110:111], v[110:111]
	v_mov_b32_e32 v149, v160
	v_mov_b32_e32 v151, v161
	v_mov_b32_e32 v137, v159
	v_mov_b32_e32 v129, v164
	v_mov_b32_e32 v127, v157
	v_pk_mov_b32 v[140:141], v[154:155], v[146:147] op_sel:[1,0]
	v_mov_b32_e32 v155, v147
	v_pk_add_f32 v[130:131], v[148:149], v[150:151]
	v_pk_add_f32 v[128:129], v[128:129], v[136:137]
	v_pk_add_f32 v[126:127], v[126:127], v[132:133]
	s_waitcnt vmcnt(0)
	v_mul_f32_e32 v156, v123, v123
	v_mul_f32_e32 v158, v125, v125
	v_pk_add_f32 v[134:135], v[140:141], v[154:155]
	v_pk_add_f32 v[128:129], v[128:129], v[130:131]
	v_pk_add_f32 v[126:127], v[126:127], v[142:143]
	v_mul_f32_e32 v162, v120, v120
	v_mul_f32_e32 v163, v121, v121
	v_mul_f32_e32 v165, v118, v118
	v_mul_f32_e32 v166, v119, v119
	v_pk_fma_f32 v[144:145], v[122:123], v[122:123], v[156:157] op_sel_hi:[1,1,0]
	v_pk_fma_f32 v[146:147], v[124:125], v[124:125], v[158:159] op_sel_hi:[1,1,0]
	v_pk_add_f32 v[134:135], v[134:135], v[134:135] op_sel:[0,1] op_sel_hi:[1,0]
	v_pk_add_f32 v[128:129], v[128:129], v[128:129] op_sel:[0,1] op_sel_hi:[1,0]
	v_add_f32_e32 v93, v126, v127
	v_mov_b32_e32 v145, v162
	v_mov_b32_e32 v147, v163
	v_mov_b32_e32 v135, v166
	v_mov_b32_e32 v129, v165
	ds_bpermute_b32 v130, v85, v93
	v_pk_add_f32 v[138:139], v[144:145], v[146:147]
	v_pk_add_f32 v[126:127], v[128:129], v[134:135]
	s_waitcnt lgkmcnt(0)
	v_add_f32_e32 v93, v93, v130
	v_pk_add_f32 v[126:127], v[126:127], v[138:139]
	ds_bpermute_b32 v128, v86, v93
	v_add_f32_e32 v126, v126, v127
	ds_bpermute_b32 v127, v85, v126
	s_waitcnt lgkmcnt(1)
	v_add_f32_e32 v93, v93, v128
	ds_bpermute_b32 v128, v87, v93
	s_waitcnt lgkmcnt(1)
	v_add_f32_e32 v126, v126, v127
	ds_bpermute_b32 v127, v86, v126
	s_waitcnt lgkmcnt(1)
	v_add_f32_e32 v93, v93, v128
	ds_bpermute_b32 v128, v88, v93
	s_waitcnt lgkmcnt(1)
	v_add_f32_e32 v126, v126, v127
	ds_bpermute_b32 v127, v87, v126
	s_waitcnt lgkmcnt(1)
	v_add_f32_e32 v93, v93, v128
	ds_bpermute_b32 v128, v89, v93
	s_waitcnt lgkmcnt(1)
	v_add_f32_e32 v126, v126, v127
	ds_bpermute_b32 v127, v88, v126
	s_waitcnt lgkmcnt(1)
	v_add_f32_e32 v93, v93, v128
	ds_bpermute_b32 v128, v90, v93
	s_waitcnt lgkmcnt(1)
	v_add_f32_e32 v126, v126, v127
	ds_bpermute_b32 v127, v89, v126
	s_waitcnt lgkmcnt(1)
	v_add_f32_e32 v93, v93, v128
	v_fmamk_f32 v93, v93, 0x3a000000, v91
	s_waitcnt lgkmcnt(0)
	v_add_f32_e32 v126, v126, v127
	ds_bpermute_b32 v127, v90, v126
	v_mul_f32_e32 v128, 0x4f800000, v93
	v_cmp_gt_f32_e32 vcc, s1, v93
	s_waitcnt lgkmcnt(0)
	v_add_f32_e32 v126, v126, v127
	v_cndmask_b32_e32 v93, v93, v128, vcc
	v_sqrt_f32_e32 v127, v93
	v_fmamk_f32 v126, v126, 0x3a000000, v91
	v_mul_f32_e32 v128, 0x4f800000, v126
	v_cmp_gt_f32_e64 s[2:3], s1, v126
	v_add_u32_e32 v129, -1, v127
	v_add_u32_e32 v130, 1, v127
	v_cndmask_b32_e64 v126, v126, v128, s[2:3]
	v_sqrt_f32_e32 v128, v126
	v_fma_f32 v131, -v129, v127, v93
	v_fma_f32 v132, -v130, v127, v93
	v_cmp_ge_f32_e64 s[4:5], 0, v131
	s_nop 1
	v_cndmask_b32_e64 v127, v127, v129, s[4:5]
	v_cmp_lt_f32_e64 s[4:5], 0, v132
	v_add_u32_e32 v129, -1, v128
	v_fma_f32 v132, -v129, v128, v126
	v_cndmask_b32_e64 v127, v127, v130, s[4:5]
	v_add_u32_e32 v130, 1, v128
	v_mul_f32_e32 v131, 0x37800000, v127
	v_fma_f32 v133, -v130, v128, v126
	v_cndmask_b32_e32 v127, v127, v131, vcc
	v_cmp_ge_f32_e32 vcc, 0, v132
	v_cmp_class_f32_e64 s[4:5], v93, v92
	s_nop 0
	v_cndmask_b32_e32 v128, v128, v129, vcc
	v_cmp_lt_f32_e32 vcc, 0, v133
	v_cndmask_b32_e64 v93, v127, v93, s[4:5]
	s_nop 0
	v_cndmask_b32_e32 v127, v128, v130, vcc
	v_div_scale_f32 v128, s[4:5], v93, v93, 1.0
	v_mul_f32_e32 v130, 0x37800000, v127
	v_rcp_f32_e32 v131, v128
	v_cndmask_b32_e64 v127, v127, v130, s[2:3]
	v_cmp_class_f32_e64 s[2:3], v126, v92
	v_div_scale_f32 v129, vcc, 1.0, v93, 1.0
	s_nop 0
	v_cndmask_b32_e64 v138, v127, v126, s[2:3]
	v_div_scale_f32 v139, s[2:3], v138, v138, 1.0
	v_rcp_f32_e32 v141, v139
	v_fma_f32 v126, -v128, v131, 1.0
	v_fmac_f32_e32 v131, v126, v131
	v_mul_f32_e32 v126, v129, v131
	v_fma_f32 v127, -v128, v126, v129
	v_fma_f32 v130, -v139, v141, 1.0
	v_div_scale_f32 v140, s[2:3], 1.0, v138, 1.0
	v_fmac_f32_e32 v126, v127, v131
	v_fmac_f32_e32 v141, v130, v141
	v_fma_f32 v127, -v128, v126, v129
	v_mul_f32_e32 v142, v140, v141
	v_div_fmas_f32 v126, v127, v131, v126
	v_fma_f32 v127, -v139, v142, v140
	v_div_fixup_f32 v126, v126, v93, 1.0
	v_fmac_f32_e32 v142, v127, v141
	v_pk_mul_f32 v[128:129], v[24:25], v[126:127] op_sel_hi:[1,0]
	v_fma_f32 v24, -v139, v142, v140
	s_mov_b64 vcc, s[2:3]
	v_pk_mul_f32 v[12:13], v[12:13], v[126:127] op_sel_hi:[1,0]
	v_pk_mul_f32 v[14:15], v[14:15], v[126:127] op_sel_hi:[1,0]
	v_pk_mul_f32 v[16:17], v[16:17], v[126:127] op_sel_hi:[1,0]
	v_pk_mul_f32 v[18:19], v[18:19], v[126:127] op_sel_hi:[1,0]
	v_pk_mul_f32 v[20:21], v[20:21], v[126:127] op_sel_hi:[1,0]
	v_pk_mul_f32 v[22:23], v[22:23], v[126:127] op_sel_hi:[1,0]
	v_pk_mul_f32 v[36:37], v[36:37], v[126:127] op_sel_hi:[1,0]
	v_pk_mul_f32 v[38:39], v[38:39], v[126:127] op_sel_hi:[1,0]
	v_pk_mul_f32 v[130:131], v[26:27], v[126:127] op_sel_hi:[1,0]
	v_pk_mul_f32 v[132:133], v[28:29], v[126:127] op_sel_hi:[1,0]
	v_pk_mul_f32 v[134:135], v[30:31], v[126:127] op_sel_hi:[1,0]
	v_pk_mul_f32 v[40:41], v[40:41], v[126:127] op_sel_hi:[1,0]
	v_pk_mul_f32 v[42:43], v[42:43], v[126:127] op_sel_hi:[1,0]
	v_pk_mul_f32 v[136:137], v[32:33], v[126:127] op_sel_hi:[1,0]
	v_pk_mul_f32 v[126:127], v[34:35], v[126:127] op_sel_hi:[1,0]
	v_div_fmas_f32 v93, v24, v141, v142
	v_pk_mul_f32 v[14:15], v[10:11], v[14:15]
	v_pk_mul_f32 v[12:13], v[8:9], v[12:13]
	v_pk_mul_f32 v[26:27], v[46:47], v[38:39]
	v_pk_mul_f32 v[38:39], v[58:59], v[42:43]
	v_pk_mul_f32 v[42:43], v[62:63], v[126:127]
	v_div_fixup_f32 v126, v93, v138, 1.0
	global_store_dwordx4 v[78:79], v[12:15], off offset:-4096 sc1
	v_pk_mul_f32 v[110:111], v[110:111], v[126:127] op_sel_hi:[1,0]
	v_pk_mul_f32 v[112:113], v[112:113], v[126:127] op_sel_hi:[1,0]
	v_pk_mul_f32 v[12:13], v[94:95], v[126:127] op_sel_hi:[1,0]
	v_pk_mul_f32 v[14:15], v[96:97], v[126:127] op_sel_hi:[1,0]
	v_pk_mul_f32 v[94:95], v[98:99], v[126:127] op_sel_hi:[1,0]
	v_pk_mul_f32 v[96:97], v[100:101], v[126:127] op_sel_hi:[1,0]
	v_pk_mul_f32 v[98:99], v[102:103], v[126:127] op_sel_hi:[1,0]
	v_pk_mul_f32 v[100:101], v[104:105], v[126:127] op_sel_hi:[1,0]
	v_pk_mul_f32 v[102:103], v[106:107], v[126:127] op_sel_hi:[1,0]
	v_pk_mul_f32 v[104:105], v[108:109], v[126:127] op_sel_hi:[1,0]
	v_pk_mul_f32 v[106:107], v[114:115], v[126:127] op_sel_hi:[1,0]
	v_pk_mul_f32 v[108:109], v[116:117], v[126:127] op_sel_hi:[1,0]
	v_pk_mul_f32 v[114:115], v[122:123], v[126:127] op_sel_hi:[1,0]
	v_pk_mul_f32 v[116:117], v[124:125], v[126:127] op_sel_hi:[1,0]
	v_pk_mul_f32 v[118:119], v[118:119], v[126:127] op_sel_hi:[1,0]
	v_pk_mul_f32 v[120:121], v[120:121], v[126:127] op_sel_hi:[1,0]
	v_pk_mul_f32 v[10:11], v[10:11], v[14:15]
	v_pk_mul_f32 v[8:9], v[8:9], v[12:13]
	v_pk_mul_f32 v[18:19], v[6:7], v[18:19]
	v_pk_mul_f32 v[16:17], v[4:5], v[16:17]
	v_pk_mul_f32 v[22:23], v[2:3], v[22:23]
	v_pk_mul_f32 v[20:21], v[0:1], v[20:21]
	v_pk_mul_f32 v[24:25], v[44:45], v[36:37]
	v_pk_mul_f32 v[30:31], v[50:51], v[130:131]
	v_pk_mul_f32 v[28:29], v[48:49], v[128:129]
	v_pk_mul_f32 v[34:35], v[54:55], v[134:135]
	v_pk_mul_f32 v[32:33], v[52:53], v[132:133]
	v_pk_mul_f32 v[36:37], v[56:57], v[40:41]
	v_pk_mul_f32 v[40:41], v[60:61], v[136:137]
	v_pk_mul_f32 v[6:7], v[6:7], v[96:97]
	v_pk_mul_f32 v[4:5], v[4:5], v[94:95]
	v_pk_mul_f32 v[2:3], v[2:3], v[100:101]
	v_pk_mul_f32 v[0:1], v[0:1], v[98:99]
	v_pk_mul_f32 v[14:15], v[46:47], v[104:105]
	v_pk_mul_f32 v[12:13], v[44:45], v[102:103]
	v_pk_mul_f32 v[46:47], v[50:51], v[108:109]
	v_pk_mul_f32 v[44:45], v[48:49], v[106:107]
	v_pk_mul_f32 v[50:51], v[54:55], v[112:113]
	v_pk_mul_f32 v[48:49], v[52:53], v[110:111]
	v_pk_mul_f32 v[54:55], v[58:59], v[116:117]
	v_pk_mul_f32 v[52:53], v[56:57], v[114:115]
	v_pk_mul_f32 v[58:59], v[62:63], v[120:121]
	v_pk_mul_f32 v[56:57], v[60:61], v[118:119]
	global_store_dwordx4 v[82:83], v[8:11], off sc1
	global_store_dwordx4 v[78:79], v[16:19], off offset:-3072 sc1
	global_store_dwordx4 v[82:83], v[4:7], off offset:1024 sc1
	global_store_dwordx4 v[78:79], v[20:23], off offset:-2048 sc1
	global_store_dwordx4 v[82:83], v[0:3], off offset:2048 sc1
	global_store_dwordx4 v[78:79], v[24:27], off offset:-1024 sc1
	global_store_dwordx4 v[82:83], v[12:15], off offset:3072 sc1
	global_store_dwordx4 v[78:79], v[28:31], off sc1
	global_store_dwordx4 v[80:81], v[44:47], off sc1
	global_store_dwordx4 v[78:79], v[32:35], off offset:1024 sc1
	global_store_dwordx4 v[80:81], v[48:51], off offset:1024 sc1
	global_store_dwordx4 v[78:79], v[36:39], off offset:2048 sc1
	global_store_dwordx4 v[80:81], v[52:55], off offset:2048 sc1
	global_store_dwordx4 v[78:79], v[40:43], off offset:3072 sc1
	global_store_dwordx4 v[80:81], v[56:59], off offset:3072 sc1
	v_lshl_add_u64 v[78:79], v[78:79], 0, s[16:17]
	s_cbranch_scc1 .LBB0_702
	v_readlane_b32 s0, v254, 0
	s_add_i32 s2, s0, s6
	s_cmpk_gt_i32 s2, 0x3fff
	s_cbranch_scc0 .LBB0_705
	s_branch .LBB0_706

.LBB0_705:
	s_load_dwordx2 s[0:1], s[88:89], 0x90
	s_ashr_i32 s3, s2, 31
	s_lshl_b64 s[2:3], s[2:3], 13
	v_xor_b32_e32 v61, 4, v84
	s_waitcnt lgkmcnt(0)
	s_add_u32 s0, s0, s2
	s_addc_u32 s1, s1, s3
	v_lshl_add_u64 v[34:35], v[66:67], 4, s[0:1]
	global_load_dwordx4 v[28:31], v[34:35], off
	global_load_dwordx4 v[20:23], v[34:35], off offset:1024
	global_load_dwordx4 v[24:27], v[34:35], off offset:2048
	global_load_dwordx4 v[4:7], v[34:35], off offset:3072
	s_movk_i32 s2, 0x1000
	v_add_co_u32_e32 v32, vcc, s2, v34
	s_mov_b32 s0, 0xf800000
	s_nop 0
	v_addc_co_u32_e32 v33, vcc, 0, v35, vcc
	global_load_dwordx4 v[8:11], v[32:33], off
	global_load_dwordx4 v[16:19], v[32:33], off offset:1024
	global_load_dwordx4 v[0:3], v[32:33], off offset:3072
	global_load_dwordx4 v[12:15], v[32:33], off offset:2048
	global_load_dwordx4 v[36:39], v[64:65], off
	s_waitcnt vmcnt(8)
	v_mov_b32_e32 v42, v29
	s_waitcnt vmcnt(7)
	v_mov_b32_e32 v43, v21
	v_mov_b32_e32 v46, v31
	v_mov_b32_e32 v47, v23
	v_mov_b32_e32 v40, v28
	v_mov_b32_e32 v41, v20
	v_mov_b32_e32 v44, v30
	v_mov_b32_e32 v45, v22
	s_waitcnt vmcnt(6)
	v_pk_mul_f32 v[48:49], v[26:27], v[26:27]
	v_pk_mul_f32 v[50:51], v[24:25], v[24:25]
	v_pk_mul_f32 v[42:43], v[42:43], v[42:43]
	v_pk_mul_f32 v[46:47], v[46:47], v[46:47]
	v_pk_mov_b32 v[56:57], v[50:51], v[48:49] op_sel:[1,0]
	v_mov_b32_e32 v51, v49
	v_pk_fma_f32 v[40:41], v[40:41], v[40:41], v[42:43]
	v_pk_fma_f32 v[42:43], v[44:45], v[44:45], v[46:47]
	s_waitcnt vmcnt(5)
	v_mul_f32_e32 v52, v5, v5
	v_mul_f32_e32 v54, v7, v7
	v_pk_add_f32 v[44:45], v[56:57], v[50:51]
	v_pk_add_f32 v[40:41], v[40:41], v[42:43]
	s_waitcnt vmcnt(4)
	v_mul_f32_e32 v63, v8, v8
	v_mul_f32_e32 v66, v9, v9
	v_mul_f32_e32 v67, v10, v10
	v_mul_f32_e32 v68, v11, v11
	v_pk_fma_f32 v[48:49], v[4:5], v[4:5], v[52:53] op_sel_hi:[1,1,0]
	v_pk_fma_f32 v[52:53], v[6:7], v[6:7], v[54:55] op_sel_hi:[1,1,0]
	v_pk_add_f32 v[42:43], v[44:45], v[44:45] op_sel:[0,1] op_sel_hi:[1,0]
	v_pk_add_f32 v[40:41], v[40:41], v[40:41] op_sel:[0,1] op_sel_hi:[1,0]
	s_waitcnt vmcnt(3)
	v_pk_mul_f32 v[54:55], v[18:19], v[18:19]
	v_pk_mul_f32 v[58:59], v[16:17], v[16:17]
	v_mov_b32_e32 v49, v67
	v_mov_b32_e32 v53, v68
	v_mov_b32_e32 v43, v66
	v_mov_b32_e32 v41, v63
	v_pk_mov_b32 v[46:47], v[58:59], v[54:55] op_sel:[1,0]
	v_mov_b32_e32 v59, v55
	v_pk_add_f32 v[44:45], v[48:49], v[52:53]
	v_pk_add_f32 v[40:41], v[40:41], v[42:43]
	s_waitcnt vmcnt(1)
	v_mul_f32_e32 v60, v13, v13
	v_mul_f32_e32 v62, v15, v15
	v_pk_add_f32 v[46:47], v[46:47], v[58:59]
	v_pk_add_f32 v[40:41], v[40:41], v[44:45]
	v_mul_f32_e32 v69, v0, v0
	v_mul_f32_e32 v70, v1, v1
	v_mul_f32_e32 v71, v2, v2
	v_mul_f32_e32 v72, v3, v3
	v_pk_fma_f32 v[50:51], v[12:13], v[12:13], v[60:61] op_sel_hi:[1,1,0]
	v_pk_fma_f32 v[54:55], v[14:15], v[14:15], v[62:63] op_sel_hi:[1,1,0]
	v_pk_add_f32 v[46:47], v[46:47], v[46:47] op_sel:[0,1] op_sel_hi:[1,0]
	v_pk_add_f32 v[40:41], v[40:41], v[40:41] op_sel:[0,1] op_sel_hi:[1,0]
	v_mov_b32_e32 v51, v71
	v_mov_b32_e32 v55, v72
	v_mov_b32_e32 v47, v70
	v_mov_b32_e32 v41, v69
	v_pk_add_f32 v[48:49], v[50:51], v[54:55]
	v_pk_add_f32 v[40:41], v[40:41], v[46:47]
	v_xor_b32_e32 v42, 8, v84
	v_pk_add_f32 v[40:41], v[40:41], v[48:49]
	s_nop 0
	v_add_f32_e32 v40, v40, v41
	ds_bpermute_b32 v41, v61, v40
	s_waitcnt lgkmcnt(0)
	v_add_f32_e32 v40, v40, v41
	ds_bpermute_b32 v41, v42, v40
	v_xor_b32_e32 v42, 16, v84
	s_waitcnt lgkmcnt(0)
	v_add_f32_e32 v40, v40, v41
	ds_bpermute_b32 v41, v42, v40
	v_xor_b32_e32 v42, 32, v84
	s_waitcnt lgkmcnt(0)
	v_add_f32_e32 v40, v40, v41
	ds_bpermute_b32 v41, v42, v40
	v_xor_b32_e32 v42, 64, v84
	s_waitcnt lgkmcnt(0)
	v_add_f32_e32 v40, v40, v41
	ds_bpermute_b32 v41, v42, v40
	v_xor_b32_e32 v42, 0x80, v84
	s_waitcnt lgkmcnt(0)
	v_add_f32_e32 v40, v40, v41
	ds_bpermute_b32 v41, v42, v40
	v_mov_b32_e32 v42, 0x358637bd
	s_waitcnt lgkmcnt(0)
	v_add_f32_e32 v40, v40, v41
	v_fmac_f32_e32 v42, 0x3a000000, v40
	v_mul_f32_e32 v40, 0x4f800000, v42
	v_cmp_gt_f32_e32 vcc, s0, v42
	s_nop 1
	v_cndmask_b32_e32 v40, v42, v40, vcc
	v_sqrt_f32_e32 v41, v40
	v_mov_b32_e32 v42, 0x260
	v_add_u32_e32 v43, -1, v41
	v_add_u32_e32 v44, 1, v41
	v_fma_f32 v45, -v43, v41, v40
	v_fma_f32 v46, -v44, v41, v40
	v_cmp_ge_f32_e64 s[0:1], 0, v45
	s_nop 1
	v_cndmask_b32_e64 v41, v41, v43, s[0:1]
	v_cmp_lt_f32_e64 s[0:1], 0, v46
	s_nop 1
	v_cndmask_b32_e64 v41, v41, v44, s[0:1]
	v_mul_f32_e32 v43, 0x37800000, v41
	v_cndmask_b32_e32 v41, v41, v43, vcc
	v_cmp_class_f32_e32 vcc, v40, v42
	s_nop 1
	v_cndmask_b32_e32 v40, v41, v40, vcc
	v_div_scale_f32 v41, s[0:1], v40, v40, 1.0
	v_rcp_f32_e32 v42, v41
	v_div_scale_f32 v43, vcc, 1.0, v40, 1.0
	v_fma_f32 v44, -v41, v42, 1.0
	v_fmac_f32_e32 v42, v44, v42
	v_mul_f32_e32 v44, v43, v42
	v_fma_f32 v45, -v41, v44, v43
	v_fmac_f32_e32 v44, v45, v42
	v_fma_f32 v41, -v41, v44, v43
	v_div_fmas_f32 v41, v41, v42, v44
	v_div_fixup_f32 v40, v41, v40, 1.0
	v_pk_mul_f32 v[28:29], v[28:29], v[40:41] op_sel_hi:[1,0]
	v_pk_mul_f32 v[30:31], v[30:31], v[40:41] op_sel_hi:[1,0]
	s_waitcnt vmcnt(0)
	v_pk_mul_f32 v[28:29], v[36:37], v[28:29]
	v_pk_mul_f32 v[30:31], v[38:39], v[30:31]
	global_store_dwordx4 v[34:35], v[28:31], off sc1
	global_load_dwordx4 v[28:31], v[64:65], off offset:1024
	v_pk_mul_f32 v[22:23], v[22:23], v[40:41] op_sel_hi:[1,0]
	v_pk_mul_f32 v[20:21], v[20:21], v[40:41] op_sel_hi:[1,0]
	v_pk_mul_f32 v[26:27], v[26:27], v[40:41] op_sel_hi:[1,0]
	v_pk_mul_f32 v[24:25], v[24:25], v[40:41] op_sel_hi:[1,0]
	v_pk_mul_f32 v[6:7], v[6:7], v[40:41] op_sel_hi:[1,0]
	v_pk_mul_f32 v[4:5], v[4:5], v[40:41] op_sel_hi:[1,0]
	v_pk_mul_f32 v[10:11], v[10:11], v[40:41] op_sel_hi:[1,0]
	v_pk_mul_f32 v[8:9], v[8:9], v[40:41] op_sel_hi:[1,0]
	v_pk_mul_f32 v[2:3], v[2:3], v[40:41] op_sel_hi:[1,0]
	v_pk_mul_f32 v[0:1], v[0:1], v[40:41] op_sel_hi:[1,0]
	s_waitcnt vmcnt(0)
	v_pk_mul_f32 v[20:21], v[28:29], v[20:21]
	v_pk_mul_f32 v[22:23], v[30:31], v[22:23]
	global_store_dwordx4 v[34:35], v[20:23], off offset:1024 sc1
	global_load_dwordx4 v[20:23], v[64:65], off offset:2048
	s_waitcnt vmcnt(0)
	v_pk_mul_f32 v[20:21], v[20:21], v[24:25]
	v_pk_mul_f32 v[22:23], v[22:23], v[26:27]
	global_store_dwordx4 v[34:35], v[20:23], off offset:2048 sc1
	global_load_dwordx4 v[20:23], v[64:65], off offset:3072
	v_add_co_u32_e32 v24, vcc, s2, v64
	s_waitcnt vmcnt(0)
	v_pk_mul_f32 v[4:5], v[20:21], v[4:5]
	v_pk_mul_f32 v[6:7], v[22:23], v[6:7]
	v_addc_co_u32_e32 v25, vcc, 0, v65, vcc
	global_store_dwordx4 v[34:35], v[4:7], off offset:3072 sc1
	global_load_dwordx4 v[4:7], v[24:25], off
	s_waitcnt vmcnt(0)
	v_pk_mul_f32 v[4:5], v[4:5], v[8:9]
	v_pk_mul_f32 v[6:7], v[6:7], v[10:11]
	global_store_dwordx4 v[32:33], v[4:7], off sc1
	global_load_dwordx4 v[4:7], v[24:25], off offset:1024
	v_pk_mul_f32 v[8:9], v[18:19], v[40:41] op_sel_hi:[1,0]
	v_pk_mul_f32 v[10:11], v[16:17], v[40:41] op_sel_hi:[1,0]
	s_waitcnt vmcnt(0)
	v_pk_mul_f32 v[6:7], v[6:7], v[8:9]
	v_pk_mul_f32 v[4:5], v[4:5], v[10:11]
	global_store_dwordx4 v[32:33], v[4:7], off offset:1024 sc1
	global_load_dwordx4 v[4:7], v[24:25], off offset:2048
	v_pk_mul_f32 v[8:9], v[14:15], v[40:41] op_sel_hi:[1,0]
	v_pk_mul_f32 v[10:11], v[12:13], v[40:41] op_sel_hi:[1,0]
	s_waitcnt vmcnt(0)
	v_pk_mul_f32 v[6:7], v[8:9], v[6:7]
	v_pk_mul_f32 v[4:5], v[10:11], v[4:5]
	global_store_dwordx4 v[32:33], v[4:7], off offset:2048 sc1
	global_load_dwordx4 v[4:7], v[24:25], off offset:3072
	s_waitcnt vmcnt(0)
	v_pk_mul_f32 v[0:1], v[0:1], v[4:5]
	v_pk_mul_f32 v[2:3], v[2:3], v[6:7]
	global_store_dwordx4 v[32:33], v[0:3], off offset:3072 sc1
